# GEMM k-loops: first fragment reads interleaved with the LDS-DMA issue in place of the m0 wait-state nops
# baseline (speedup 1.0000x reference)
.LBB0_231:
	s_add_i32 s47, s48, 0x8000
	s_and_b32 s27, s48, 0x8000
	s_and_b32 s50, s47, 0x8000
	s_add_i32 s48, s27, 0
	s_add_i32 s27, s50, 0
	s_add_u32 s70, s27, s71
	s_mov_b32 m0, s70
	s_waitcnt vmcnt(0) lgkmcnt(0)
	s_barrier
	v_add3_u32 v145, s48, v86, v87
	v_add3_u32 v208, s48, v87, v88
	v_add3_u32 v209, s48, v86, v89
	v_add3_u32 v210, s48, v88, v89
	global_load_lds_dwordx4 v244, s[96:97]
	s_add_u32 m0, s70, 0x4000
	ds_read_b128 v[104:107], v208
	global_load_lds_dwordx4 v245, s[72:73]
	s_add_u32 m0, s70, 0x1000
	ds_read_b128 v[100:103], v145 offset:16384
	global_load_lds_dwordx4 v246, s[96:97]
	s_add_u32 m0, s70, 0x5000
	ds_read_b128 v[108:111], v145 offset:18432
	global_load_lds_dwordx4 v247, s[72:73]
	s_add_u32 m0, s70, 0x2000
	ds_read_b128 v[164:167], v208 offset:2048
	global_load_lds_dwordx4 v248, s[96:97]
	s_add_u32 m0, s70, 0x6000
	ds_read_b128 v[112:115], v145 offset:20480
	global_load_lds_dwordx4 v249, s[72:73]
	s_add_u32 m0, s70, 0x3000
	ds_read_b128 v[116:119], v145 offset:22528
	global_load_lds_dwordx4 v250, s[96:97]
	s_add_u32 m0, s70, 0x7000
	ds_read_b128 v[120:123], v145 offset:24576
	global_load_lds_dwordx4 v251, s[72:73]
	s_add_u32 s96, s96, 0x80
	s_addc_u32 s97, s97, 0
	s_add_u32 s72, s72, 0x80
	s_addc_u32 s73, s73, 0
	ds_read_b128 v[124:127], v145 offset:26624
	ds_read_b128 v[128:131], v145 offset:28672
	ds_read_b128 v[132:135], v145 offset:30720
	ds_read_b128 v[200:203], v210
	ds_read_b128 v[168:171], v209 offset:16384
	ds_read_b128 v[172:175], v209 offset:18432
	ds_read_b128 v[204:207], v210 offset:2048
	ds_read_b128 v[176:179], v209 offset:20480
	ds_read_b128 v[180:183], v209 offset:22528
	ds_read_b128 v[184:187], v209 offset:24576
	ds_read_b128 v[188:191], v209 offset:26624
	ds_read_b128 v[192:195], v209 offset:28672
	ds_read_b128 v[196:199], v209 offset:30720
	s_add_u32 s24, s24, 0x80
	s_addc_u32 s25, s25, 0
	s_cmpk_eq_i32 s24, 0x780
	s_mov_b32 s48, s47
	s_waitcnt lgkmcnt(15)
	v_mfma_f32_16x16x32_bf16 v[60:63], v[100:103], v[104:107], v[60:63]
	v_mfma_f32_16x16x32_bf16 v[56:59], v[108:111], v[104:107], v[56:59]
	v_mfma_f32_16x16x32_bf16 v[24:27], v[100:103], v[164:167], v[24:27]
	v_mfma_f32_16x16x32_bf16 v[20:23], v[108:111], v[164:167], v[20:23]
	v_mfma_f32_16x16x32_bf16 v[52:55], v[112:115], v[104:107], v[52:55]
	v_mfma_f32_16x16x32_bf16 v[16:19], v[112:115], v[164:167], v[16:19]
	s_waitcnt lgkmcnt(14)
	v_mfma_f32_16x16x32_bf16 v[48:51], v[116:119], v[104:107], v[48:51]
	v_mfma_f32_16x16x32_bf16 v[12:15], v[116:119], v[164:167], v[12:15]
	s_waitcnt lgkmcnt(13)
	v_mfma_f32_16x16x32_bf16 v[44:47], v[120:123], v[104:107], v[44:47]
	v_mfma_f32_16x16x32_bf16 v[8:11], v[120:123], v[164:167], v[8:11]
	s_waitcnt lgkmcnt(12)
	v_mfma_f32_16x16x32_bf16 v[40:43], v[124:127], v[104:107], v[40:43]
	v_mfma_f32_16x16x32_bf16 v[4:7], v[124:127], v[164:167], v[4:7]
	s_waitcnt lgkmcnt(11)
	v_mfma_f32_16x16x32_bf16 v[36:39], v[128:131], v[104:107], v[36:39]
	v_mfma_f32_16x16x32_bf16 v[0:3], v[128:131], v[164:167], v[0:3]
	s_waitcnt lgkmcnt(10)
	v_mfma_f32_16x16x32_bf16 v[32:35], v[132:135], v[104:107], v[32:35]
	v_mfma_f32_16x16x32_bf16 v[28:31], v[132:135], v[164:167], v[28:31]
	s_waitcnt lgkmcnt(8)
	v_mfma_f32_16x16x32_bf16 v[60:63], v[168:171], v[200:203], v[60:63]
	s_waitcnt lgkmcnt(7)
	v_mfma_f32_16x16x32_bf16 v[56:59], v[172:175], v[200:203], v[56:59]
	s_waitcnt lgkmcnt(6)
	v_mfma_f32_16x16x32_bf16 v[24:27], v[168:171], v[204:207], v[24:27]
	v_mfma_f32_16x16x32_bf16 v[20:23], v[172:175], v[204:207], v[20:23]
	s_waitcnt lgkmcnt(5)
	v_mfma_f32_16x16x32_bf16 v[52:55], v[176:179], v[200:203], v[52:55]
	v_mfma_f32_16x16x32_bf16 v[16:19], v[176:179], v[204:207], v[16:19]
	s_waitcnt lgkmcnt(4)
	v_mfma_f32_16x16x32_bf16 v[48:51], v[180:183], v[200:203], v[48:51]
	v_mfma_f32_16x16x32_bf16 v[12:15], v[180:183], v[204:207], v[12:15]
	s_waitcnt lgkmcnt(3)
	v_mfma_f32_16x16x32_bf16 v[44:47], v[184:187], v[200:203], v[44:47]
	v_mfma_f32_16x16x32_bf16 v[8:11], v[184:187], v[204:207], v[8:11]
	s_waitcnt lgkmcnt(2)
	v_mfma_f32_16x16x32_bf16 v[40:43], v[188:191], v[200:203], v[40:43]
	v_mfma_f32_16x16x32_bf16 v[4:7], v[188:191], v[204:207], v[4:7]
	s_waitcnt lgkmcnt(1)
	v_mfma_f32_16x16x32_bf16 v[36:39], v[192:195], v[200:203], v[36:39]
	v_mfma_f32_16x16x32_bf16 v[0:3], v[192:195], v[204:207], v[0:3]
	s_waitcnt lgkmcnt(0)
	v_mfma_f32_16x16x32_bf16 v[32:35], v[196:199], v[200:203], v[32:35]
	v_mfma_f32_16x16x32_bf16 v[28:31], v[196:199], v[204:207], v[28:31]
	s_cbranch_scc0 .LBB0_231
	v_add_u32_e32 v64, s27, v86
	v_add_u32_e32 v136, v64, v87
	v_add3_u32 v108, s27, v87, v88
	s_waitcnt vmcnt(0)
	s_barrier
	ds_read_b128 v[80:83], v136 offset:16384
	ds_read_b128 v[100:103], v136 offset:18432
	ds_read_b128 v[104:107], v108
	ds_read_b128 v[108:111], v108 offset:2048
	ds_read_b128 v[112:115], v136 offset:20480
	ds_read_b128 v[116:119], v136 offset:22528
	ds_read_b128 v[128:131], v136 offset:28672
	s_waitcnt lgkmcnt(2)
	v_mfma_f32_16x16x32_bf16 v[120:123], v[112:115], v[104:107], v[52:55]
	s_nop 2
	ds_read_b128 v[52:55], v136 offset:24576
	ds_read_b128 v[124:127], v136 offset:26624
	s_cmp_gt_i32 s26, 11
	s_waitcnt lgkmcnt(0)
	v_mfma_f32_16x16x32_bf16 v[132:135], v[124:127], v[104:107], v[40:43]
	s_nop 2
	ds_read_b128 v[40:43], v136 offset:30720
	s_cselect_b64 s[24:25], -1, 0
	s_cmp_lt_i32 s26, 12
	v_mfma_f32_16x16x32_bf16 v[60:63], v[80:83], v[104:107], v[60:63]
	s_cselect_b64 s[48:49], -1, 0
	v_mfma_f32_16x16x32_bf16 v[56:59], v[100:103], v[104:107], v[56:59]
	v_mfma_f32_16x16x32_bf16 v[48:51], v[116:119], v[104:107], v[48:51]
	v_mfma_f32_16x16x32_bf16 v[44:47], v[52:55], v[104:107], v[44:47]
	v_mfma_f32_16x16x32_bf16 v[136:139], v[128:131], v[104:107], v[36:39]
	s_waitcnt lgkmcnt(0)
	v_mfma_f32_16x16x32_bf16 v[32:35], v[40:43], v[104:107], v[32:35]
	v_mfma_f32_16x16x32_bf16 v[104:107], v[52:55], v[108:111], v[8:11]
	s_nop 2
	v_add_u32_e32 v8, v64, v89
	v_mfma_f32_16x16x32_bf16 v[24:27], v[80:83], v[108:111], v[24:27]
	v_add3_u32 v9, s27, v89, v88
	v_lshl_or_b32 v64, s26, 7, v90
	s_sub_i32 s26, s26, 18
	v_mfma_f32_16x16x32_bf16 v[80:83], v[112:115], v[108:111], v[16:19]
	s_cmp_lt_u32 s26, 8
	s_cselect_b64 s[26:27], -1, 0
	s_or_b64 s[48:49], s[48:49], s[26:27]
	v_mfma_f32_16x16x32_bf16 v[112:115], v[124:127], v[108:111], v[4:7]
	s_mov_b64 s[26:27], -1
	s_andn2_b64 vcc, exec, s[48:49]
	s_nop 0
	ds_read_b128 v[4:7], v8 offset:16384
	v_mfma_f32_16x16x32_bf16 v[20:23], v[100:103], v[108:111], v[20:23]
	v_mfma_f32_16x16x32_bf16 v[100:103], v[116:119], v[108:111], v[12:15]
	v_mfma_f32_16x16x32_bf16 v[116:119], v[128:131], v[108:111], v[0:3]
	ds_read_b128 v[124:127], v8 offset:18432
	s_nop 1
	ds_read_b128 v[0:3], v9
	ds_read_b128 v[128:131], v9 offset:2048
	ds_read_b128 v[140:143], v8 offset:22528
	ds_read_b128 v[146:149], v8 offset:28672
	s_waitcnt lgkmcnt(3)
	v_mfma_f32_16x16x32_bf16 v[52:55], v[4:7], v[0:3], v[60:63]
	s_nop 2
	ds_read_b128 v[60:63], v8 offset:20480
	v_mfma_f32_16x16x32_bf16 v[108:111], v[40:43], v[108:111], v[28:31]
	s_waitcnt lgkmcnt(0)
	v_mfma_f32_16x16x32_bf16 v[36:39], v[60:63], v[0:3], v[120:123]
	s_nop 2
	ds_read_b128 v[120:123], v8 offset:24576
	v_mfma_f32_16x16x32_bf16 v[40:43], v[140:143], v[0:3], v[48:51]
	s_nop 2
	ds_read_b128 v[48:51], v8 offset:26624
	s_waitcnt lgkmcnt(0)
	v_mfma_f32_16x16x32_bf16 v[16:19], v[48:51], v[0:3], v[132:135]
	s_nop 2
	ds_read_b128 v[132:135], v8 offset:30720
	v_mfma_f32_16x16x32_bf16 v[56:59], v[124:127], v[0:3], v[56:59]
	v_mfma_f32_16x16x32_bf16 v[12:15], v[120:123], v[0:3], v[44:47]
	v_mfma_f32_16x16x32_bf16 v[8:11], v[146:149], v[0:3], v[136:139]
	s_waitcnt lgkmcnt(0)
	v_mfma_f32_16x16x32_bf16 v[0:3], v[132:135], v[0:3], v[32:35]
	v_mfma_f32_16x16x32_bf16 v[28:31], v[4:7], v[128:131], v[24:27]
	v_mfma_f32_16x16x32_bf16 v[20:23], v[124:127], v[128:131], v[20:23]
	v_mfma_f32_16x16x32_bf16 v[4:7], v[60:63], v[128:131], v[80:83]
	v_mfma_f32_16x16x32_bf16 v[24:27], v[140:143], v[128:131], v[100:103]
	s_nop 1
	v_lshl_add_u32 v80, s46, 7, v85
	v_mfma_f32_16x16x32_bf16 v[32:35], v[120:123], v[128:131], v[104:107]
	v_mfma_f32_16x16x32_bf16 v[44:47], v[48:51], v[128:131], v[112:115]
	v_mfma_f32_16x16x32_bf16 v[48:51], v[146:149], v[128:131], v[116:119]
	v_mfma_f32_16x16x32_bf16 v[60:63], v[132:135], v[128:131], v[108:111]
	s_cbranch_vccz .LBB0_240
	s_and_b32 s47, 0xffff, s45
	s_cmp_gt_u32 s47, 17
	s_cbranch_scc0 .LBB0_237
	s_cmp_eq_u32 s47, 26
	s_cselect_b64 s[26:27], -1, 0
	s_and_b64 s[48:49], s[10:11], s[26:27]
	s_and_saveexec_b64 s[26:27], s[48:49]
	s_cbranch_execz .LBB0_236
	global_load_dwordx4 v[100:103], v[72:73], off
	v_mad_i64_i32 v[82:83], s[48:49], v80, s28, v[70:71]
	v_or_b32_e32 v81, 16, v80
	s_waitcnt vmcnt(0)
	v_pk_add_f32 v[102:103], v[54:55], v[102:103]
	v_pk_add_f32 v[100:101], v[52:53], v[100:101]
	global_store_dwordx4 v[82:83], v[100:103], off
	global_load_dwordx4 v[100:103], v[72:73], off offset:16
	v_mad_i64_i32 v[82:83], s[48:49], v80, s28, v[74:75]
	s_waitcnt vmcnt(0)
	v_pk_add_f32 v[102:103], v[58:59], v[102:103]
	v_pk_add_f32 v[100:101], v[56:57], v[100:101]
	global_store_dwordx4 v[82:83], v[100:103], off
	global_load_dwordx4 v[100:103], v[72:73], off
	v_mad_i64_i32 v[82:83], s[48:49], v81, s28, v[70:71]
	s_waitcnt vmcnt(0)
	v_pk_add_f32 v[102:103], v[30:31], v[102:103]
	v_pk_add_f32 v[100:101], v[28:29], v[100:101]
	global_store_dwordx4 v[82:83], v[100:103], off
	global_load_dwordx4 v[100:103], v[72:73], off offset:16
	v_mad_i64_i32 v[82:83], s[48:49], v81, s28, v[74:75]
	s_waitcnt vmcnt(0)
	v_pk_add_f32 v[102:103], v[22:23], v[102:103]
	v_pk_add_f32 v[100:101], v[20:21], v[100:101]
	global_store_dwordx4 v[82:83], v[100:103], off

.LBB0_855:
	s_add_i32 s45, s43, 0x8000
	s_and_b32 s44, s45, 0x8000
	s_add_i32 s44, s44, 0
	s_add_u32 s86, s44, s87
	s_mov_b32 m0, s86
	s_waitcnt vmcnt(0) lgkmcnt(0)
	s_barrier
	s_and_b32 s43, s43, 0x8000
	s_add_i32 s43, s43, 0
	v_add3_u32 v212, s43, v88, v89
	v_add3_u32 v213, s43, v89, v90
	v_add3_u32 v214, s43, v88, v91
	v_add3_u32 v215, s43, v90, v91
	global_load_lds_dwordx4 v244, s[96:97]
	s_add_u32 m0, s86, 0x4000
	ds_read_b128 v[106:109], v213
	global_load_lds_dwordx4 v245, s[88:89]
	s_add_u32 m0, s86, 0x1000
	ds_read_b128 v[76:79], v212 offset:16384
	global_load_lds_dwordx4 v246, s[96:97]
	s_add_u32 m0, s86, 0x5000
	ds_read_b128 v[102:105], v212 offset:18432
	global_load_lds_dwordx4 v247, s[88:89]
	s_add_u32 m0, s86, 0x2000
	ds_read_b128 v[110:113], v213 offset:2048
	global_load_lds_dwordx4 v248, s[96:97]
	s_add_u32 m0, s86, 0x6000
	ds_read_b128 v[114:117], v212 offset:20480
	global_load_lds_dwordx4 v249, s[88:89]
	s_add_u32 m0, s86, 0x3000
	ds_read_b128 v[118:121], v212 offset:22528
	global_load_lds_dwordx4 v250, s[96:97]
	s_add_u32 m0, s86, 0x7000
	ds_read_b128 v[122:125], v212 offset:24576
	global_load_lds_dwordx4 v251, s[88:89]
	s_add_u32 s96, s96, 0x80
	s_addc_u32 s97, s97, 0
	s_add_u32 s88, s88, 0x80
	s_addc_u32 s89, s89, 0
	ds_read_b128 v[126:129], v212 offset:26624
	ds_read_b128 v[130:133], v212 offset:28672
	ds_read_b128 v[134:137], v212 offset:30720
	ds_read_b128 v[180:183], v215
	ds_read_b128 v[172:175], v214 offset:16384
	ds_read_b128 v[176:179], v214 offset:18432
	ds_read_b128 v[184:187], v215 offset:2048
	ds_read_b128 v[188:191], v214 offset:20480
	ds_read_b128 v[192:195], v214 offset:22528
	ds_read_b128 v[196:199], v214 offset:24576
	ds_read_b128 v[200:203], v214 offset:26624
	ds_read_b128 v[204:207], v214 offset:28672
	ds_read_b128 v[208:211], v214 offset:30720
	s_add_u32 s34, s34, 0x80
	s_addc_u32 s35, s35, 0
	s_cmpk_eq_i32 s34, 0x780
	s_mov_b32 s43, s45
	s_waitcnt lgkmcnt(15)
	v_mfma_f32_16x16x32_bf16 v[60:63], v[76:79], v[106:109], v[60:63]
	v_mfma_f32_16x16x32_bf16 v[56:59], v[102:105], v[106:109], v[56:59]
	v_mfma_f32_16x16x32_bf16 v[24:27], v[76:79], v[110:113], v[24:27]
	v_mfma_f32_16x16x32_bf16 v[20:23], v[102:105], v[110:113], v[20:23]
	v_mfma_f32_16x16x32_bf16 v[52:55], v[114:117], v[106:109], v[52:55]
	v_mfma_f32_16x16x32_bf16 v[16:19], v[114:117], v[110:113], v[16:19]
	s_waitcnt lgkmcnt(14)
	v_mfma_f32_16x16x32_bf16 v[48:51], v[118:121], v[106:109], v[48:51]
	v_mfma_f32_16x16x32_bf16 v[12:15], v[118:121], v[110:113], v[12:15]
	s_waitcnt lgkmcnt(13)
	v_mfma_f32_16x16x32_bf16 v[44:47], v[122:125], v[106:109], v[44:47]
	v_mfma_f32_16x16x32_bf16 v[8:11], v[122:125], v[110:113], v[8:11]
	s_waitcnt lgkmcnt(12)
	v_mfma_f32_16x16x32_bf16 v[40:43], v[126:129], v[106:109], v[40:43]
	v_mfma_f32_16x16x32_bf16 v[4:7], v[126:129], v[110:113], v[4:7]
	s_waitcnt lgkmcnt(11)
	v_mfma_f32_16x16x32_bf16 v[32:35], v[130:133], v[106:109], v[32:35]
	v_mfma_f32_16x16x32_bf16 v[0:3], v[130:133], v[110:113], v[0:3]
	s_waitcnt lgkmcnt(10)
	v_mfma_f32_16x16x32_bf16 v[28:31], v[134:137], v[106:109], v[28:31]
	v_mfma_f32_16x16x32_bf16 v[36:39], v[134:137], v[110:113], v[36:39]
	s_waitcnt lgkmcnt(8)
	v_mfma_f32_16x16x32_bf16 v[60:63], v[172:175], v[180:183], v[60:63]
	s_waitcnt lgkmcnt(7)
	v_mfma_f32_16x16x32_bf16 v[56:59], v[176:179], v[180:183], v[56:59]
	s_waitcnt lgkmcnt(6)
	v_mfma_f32_16x16x32_bf16 v[24:27], v[172:175], v[184:187], v[24:27]
	v_mfma_f32_16x16x32_bf16 v[20:23], v[176:179], v[184:187], v[20:23]
	s_waitcnt lgkmcnt(5)
	v_mfma_f32_16x16x32_bf16 v[52:55], v[188:191], v[180:183], v[52:55]
	v_mfma_f32_16x16x32_bf16 v[16:19], v[188:191], v[184:187], v[16:19]
	s_waitcnt lgkmcnt(4)
	v_mfma_f32_16x16x32_bf16 v[48:51], v[192:195], v[180:183], v[48:51]
	v_mfma_f32_16x16x32_bf16 v[12:15], v[192:195], v[184:187], v[12:15]
	s_waitcnt lgkmcnt(3)
	v_mfma_f32_16x16x32_bf16 v[44:47], v[196:199], v[180:183], v[44:47]
	v_mfma_f32_16x16x32_bf16 v[8:11], v[196:199], v[184:187], v[8:11]
	s_waitcnt lgkmcnt(2)
	v_mfma_f32_16x16x32_bf16 v[40:43], v[200:203], v[180:183], v[40:43]
	v_mfma_f32_16x16x32_bf16 v[4:7], v[200:203], v[184:187], v[4:7]
	s_waitcnt lgkmcnt(1)
	v_mfma_f32_16x16x32_bf16 v[32:35], v[204:207], v[180:183], v[32:35]
	v_mfma_f32_16x16x32_bf16 v[0:3], v[204:207], v[184:187], v[0:3]
	s_waitcnt lgkmcnt(0)
	v_mfma_f32_16x16x32_bf16 v[28:31], v[208:211], v[180:183], v[28:31]
	v_mfma_f32_16x16x32_bf16 v[36:39], v[208:211], v[184:187], v[36:39]
	s_cbranch_scc0 .LBB0_855
	v_add_u32_e32 v80, s44, v88
	v_add_u32_e32 v81, v80, v89
	v_add3_u32 v106, s44, v89, v90
	s_waitcnt vmcnt(0)
	s_barrier
	ds_read_b128 v[72:75], v81 offset:16384
	ds_read_b128 v[76:79], v81 offset:18432
	ds_read_b128 v[102:105], v106
	ds_read_b128 v[106:109], v106 offset:2048
	ds_read_b128 v[110:113], v81 offset:20480
	ds_read_b128 v[114:117], v81 offset:22528
	ds_read_b128 v[118:121], v81 offset:24576
	ds_read_b128 v[122:125], v81 offset:26624
	ds_read_b128 v[126:129], v81 offset:28672
	ds_read_b128 v[130:133], v81 offset:30720
	v_add_u32_e32 v80, v80, v91
	s_waitcnt lgkmcnt(7)
	v_mfma_f32_16x16x32_bf16 v[60:63], v[72:75], v[102:105], v[60:63]
	s_lshl_b32 s42, s42, 7
	v_mfma_f32_16x16x32_bf16 v[56:59], v[76:79], v[102:105], v[56:59]
	s_waitcnt lgkmcnt(4)
	v_mfma_f32_16x16x32_bf16 v[48:51], v[114:117], v[102:105], v[48:51]
	s_waitcnt lgkmcnt(3)
	v_mfma_f32_16x16x32_bf16 v[44:47], v[118:121], v[102:105], v[44:47]
	s_waitcnt lgkmcnt(2)
	v_mfma_f32_16x16x32_bf16 v[40:43], v[122:125], v[102:105], v[40:43]
	s_waitcnt lgkmcnt(1)
	v_mfma_f32_16x16x32_bf16 v[32:35], v[126:129], v[102:105], v[32:35]
	s_waitcnt lgkmcnt(0)
	v_mfma_f32_16x16x32_bf16 v[28:31], v[130:133], v[102:105], v[28:31]
	v_mfma_f32_16x16x32_bf16 v[24:27], v[72:75], v[106:109], v[24:27]
	ds_read_b128 v[72:75], v80 offset:16384
	v_mfma_f32_16x16x32_bf16 v[52:55], v[110:113], v[102:105], v[52:55]
	v_mfma_f32_16x16x32_bf16 v[20:23], v[76:79], v[106:109], v[20:23]
	v_mfma_f32_16x16x32_bf16 v[16:19], v[110:113], v[106:109], v[16:19]
	v_mfma_f32_16x16x32_bf16 v[12:15], v[114:117], v[106:109], v[12:15]
	v_mfma_f32_16x16x32_bf16 v[8:11], v[118:121], v[106:109], v[8:11]
	v_mfma_f32_16x16x32_bf16 v[4:7], v[122:125], v[106:109], v[4:7]
	v_mfma_f32_16x16x32_bf16 v[0:3], v[126:129], v[106:109], v[0:3]
	v_mfma_f32_16x16x32_bf16 v[102:105], v[130:133], v[106:109], v[36:39]
	s_nop 2
	v_add3_u32 v36, s44, v91, v90
	ds_read_b128 v[76:79], v80 offset:18432
	ds_read_b128 v[106:109], v36
	ds_read_b128 v[110:113], v36 offset:2048
	ds_read_b128 v[130:133], v80 offset:28672
	ds_read_b128 v[134:137], v80 offset:30720
	ds_read_b128 v[114:117], v80 offset:20480
	ds_read_b128 v[118:121], v80 offset:22528
	ds_read_b128 v[122:125], v80 offset:24576
	ds_read_b128 v[126:129], v80 offset:26624
	s_waitcnt lgkmcnt(7)
	v_mfma_f32_16x16x32_bf16 v[60:63], v[72:75], v[106:109], v[60:63]
	v_readlane_b32 s44, v252, 5
	v_readlane_b32 s48, v252, 9
	v_readlane_b32 s49, v252, 10
	s_waitcnt lgkmcnt(5)
	v_mfma_f32_16x16x32_bf16 v[36:39], v[130:133], v[106:109], v[32:35]
	v_readlane_b32 s45, v252, 6
	v_readlane_b32 s46, v252, 7
	v_readlane_b32 s47, v252, 8
	s_waitcnt lgkmcnt(4)
	v_mfma_f32_16x16x32_bf16 v[32:35], v[134:137], v[106:109], v[28:31]
	v_readlane_b32 s50, v252, 11
	v_readlane_b32 s51, v252, 12
	v_readlane_b32 s52, v252, 13
	v_mfma_f32_16x16x32_bf16 v[28:31], v[72:75], v[110:113], v[24:27]
	v_add_u32_e32 v72, s42, v82
	v_mul_hi_i32 v73, v72, s36
	v_lshrrev_b32_e32 v74, 31, v73
	v_mfma_f32_16x16x32_bf16 v[24:27], v[76:79], v[110:113], v[20:23]
	v_readlane_b32 s53, v252, 14
	v_readlane_b32 s54, v252, 15
	v_readlane_b32 s55, v252, 16
	s_waitcnt lgkmcnt(3)
	v_mfma_f32_16x16x32_bf16 v[20:23], v[114:117], v[110:113], v[16:19]
	v_readlane_b32 s56, v252, 17
	v_readlane_b32 s57, v252, 18
	v_readlane_b32 s58, v252, 19
	s_waitcnt lgkmcnt(2)
	v_mfma_f32_16x16x32_bf16 v[16:19], v[118:121], v[110:113], v[12:15]
	v_readlane_b32 s59, v252, 20
	s_waitcnt lgkmcnt(1)
	v_mfma_f32_16x16x32_bf16 v[12:15], v[122:125], v[110:113], v[8:11]
	s_waitcnt lgkmcnt(0)
	v_mfma_f32_16x16x32_bf16 v[8:11], v[126:129], v[110:113], v[4:7]
	s_nop 2
	v_ashrrev_i32_e32 v4, 11, v73
	v_mfma_f32_16x16x32_bf16 v[56:59], v[76:79], v[106:109], v[56:59]
	v_add_u32_e32 v73, v4, v74
	v_mad_i32_i24 v75, v73, s37, v72
	v_lshlrev_b32_e32 v78, 13, v73
	v_mfma_f32_16x16x32_bf16 v[52:55], v[114:117], v[106:109], v[52:55]
	v_cmp_lt_i32_e32 vcc, s38, v75
	v_mov_b64_e32 v[76:77], s[48:49]
	v_add3_u32 v74, v78, v75, s39
	v_mfma_f32_16x16x32_bf16 v[48:51], v[118:121], v[106:109], v[48:51]
	v_mfma_f32_16x16x32_bf16 v[44:47], v[122:125], v[106:109], v[44:47]
	v_mfma_f32_16x16x32_bf16 v[40:43], v[126:129], v[106:109], v[40:43]
	v_mfma_f32_16x16x32_bf16 v[0:3], v[130:133], v[110:113], v[0:3]
	v_mfma_f32_16x16x32_bf16 v[4:7], v[134:137], v[110:113], v[102:105]
	s_and_saveexec_b64 s[34:35], vcc
	s_xor_b64 s[34:35], exec, s[34:35]
	s_cbranch_execz .LBB0_858
	v_readlane_b32 s44, v252, 5
	v_readlane_b32 s45, v252, 6
	v_add3_u32 v72, v78, v75, s39
	v_readlane_b32 s46, v252, 7
	v_readlane_b32 s47, v252, 8
	v_readlane_b32 s48, v252, 9
	v_readlane_b32 s49, v252, 10
	v_readlane_b32 s50, v252, 11
	v_readlane_b32 s51, v252, 12
	v_readlane_b32 s52, v252, 13
	v_readlane_b32 s53, v252, 14
	v_readlane_b32 s54, v252, 15
	v_readlane_b32 s55, v252, 16
	v_readlane_b32 s56, v252, 17
	v_readlane_b32 s57, v252, 18
	v_readlane_b32 s58, v252, 19
	v_readlane_b32 s59, v252, 20
	v_mov_b64_e32 v[76:77], s[44:45]
	s_or_saveexec_b64 s[34:35], s[34:35]
	v_lshl_add_u32 v102, v73, 8, v75
	s_xor_b64 exec, exec, s[34:35]
	s_branch .LBB0_859

.LBB0_1006:
	s_add_i32 s37, s35, 0x8000
	s_and_b32 s36, s37, 0x8000
	s_add_i32 s36, s36, 0
	s_add_u32 s86, s36, s87
	s_mov_b32 m0, s86
	s_waitcnt vmcnt(0) lgkmcnt(0)
	s_barrier
	s_and_b32 s35, s35, 0x8000
	s_add_i32 s35, s35, 0
	v_add3_u32 v143, s35, v80, v81
	v_add3_u32 v145, s35, v81, v82
	v_add3_u32 v206, s35, v80, v83
	v_add3_u32 v207, s35, v82, v83
	global_load_lds_dwordx4 v244, s[96:97]
	s_add_u32 m0, s86, 0x4000
	ds_read_b128 v[102:105], v145
	global_load_lds_dwordx4 v245, s[88:89]
	s_add_u32 m0, s86, 0x1000
	ds_read_b128 v[94:97], v143 offset:16384
	global_load_lds_dwordx4 v246, s[96:97]
	s_add_u32 m0, s86, 0x5000
	ds_read_b128 v[98:101], v143 offset:18432
	global_load_lds_dwordx4 v247, s[88:89]
	s_add_u32 m0, s86, 0x2000
	ds_read_b128 v[106:109], v145 offset:2048
	global_load_lds_dwordx4 v248, s[96:97]
	s_add_u32 m0, s86, 0x6000
	ds_read_b128 v[110:113], v143 offset:20480
	global_load_lds_dwordx4 v249, s[88:89]
	s_add_u32 m0, s86, 0x3000
	ds_read_b128 v[114:117], v143 offset:22528
	global_load_lds_dwordx4 v250, s[96:97]
	s_add_u32 m0, s86, 0x7000
	ds_read_b128 v[118:121], v143 offset:24576
	global_load_lds_dwordx4 v251, s[88:89]
	s_add_u32 s96, s96, 0x80
	s_addc_u32 s97, s97, 0
	s_add_u32 s88, s88, 0x80
	s_addc_u32 s89, s89, 0
	ds_read_b128 v[122:125], v143 offset:26624
	ds_read_b128 v[126:129], v143 offset:28672
	ds_read_b128 v[130:133], v143 offset:30720
	ds_read_b128 v[174:177], v207
	ds_read_b128 v[166:169], v206 offset:16384
	ds_read_b128 v[170:173], v206 offset:18432
	ds_read_b128 v[178:181], v207 offset:2048
	ds_read_b128 v[182:185], v206 offset:20480
	ds_read_b128 v[186:189], v206 offset:22528
	ds_read_b128 v[190:193], v206 offset:24576
	ds_read_b128 v[194:197], v206 offset:26624
	ds_read_b128 v[198:201], v206 offset:28672
	ds_read_b128 v[202:205], v206 offset:30720
	s_add_u32 s26, s26, 0x80
	s_addc_u32 s27, s27, 0
	s_cmpk_eq_i32 s26, 0x780
	s_mov_b32 s35, s37
	s_waitcnt lgkmcnt(15)
	v_mfma_f32_16x16x32_bf16 v[60:63], v[94:97], v[102:105], v[60:63]
	v_mfma_f32_16x16x32_bf16 v[56:59], v[98:101], v[102:105], v[56:59]
	v_mfma_f32_16x16x32_bf16 v[28:31], v[94:97], v[106:109], v[28:31]
	v_mfma_f32_16x16x32_bf16 v[24:27], v[98:101], v[106:109], v[24:27]
	v_mfma_f32_16x16x32_bf16 v[52:55], v[110:113], v[102:105], v[52:55]
	v_mfma_f32_16x16x32_bf16 v[16:19], v[110:113], v[106:109], v[16:19]
	s_waitcnt lgkmcnt(14)
	v_mfma_f32_16x16x32_bf16 v[48:51], v[114:117], v[102:105], v[48:51]
	v_mfma_f32_16x16x32_bf16 v[12:15], v[114:117], v[106:109], v[12:15]
	s_waitcnt lgkmcnt(13)
	v_mfma_f32_16x16x32_bf16 v[44:47], v[118:121], v[102:105], v[44:47]
	v_mfma_f32_16x16x32_bf16 v[8:11], v[118:121], v[106:109], v[8:11]
	s_waitcnt lgkmcnt(12)
	v_mfma_f32_16x16x32_bf16 v[40:43], v[122:125], v[102:105], v[40:43]
	v_mfma_f32_16x16x32_bf16 v[4:7], v[122:125], v[106:109], v[4:7]
	s_waitcnt lgkmcnt(11)
	v_mfma_f32_16x16x32_bf16 v[36:39], v[126:129], v[102:105], v[36:39]
	v_mfma_f32_16x16x32_bf16 v[0:3], v[126:129], v[106:109], v[0:3]
	s_waitcnt lgkmcnt(10)
	v_mfma_f32_16x16x32_bf16 v[32:35], v[130:133], v[102:105], v[32:35]
	v_mfma_f32_16x16x32_bf16 v[20:23], v[130:133], v[106:109], v[20:23]
	s_waitcnt lgkmcnt(8)
	v_mfma_f32_16x16x32_bf16 v[60:63], v[166:169], v[174:177], v[60:63]
	s_waitcnt lgkmcnt(7)
	v_mfma_f32_16x16x32_bf16 v[56:59], v[170:173], v[174:177], v[56:59]
	s_waitcnt lgkmcnt(6)
	v_mfma_f32_16x16x32_bf16 v[28:31], v[166:169], v[178:181], v[28:31]
	v_mfma_f32_16x16x32_bf16 v[24:27], v[170:173], v[178:181], v[24:27]
	s_waitcnt lgkmcnt(5)
	v_mfma_f32_16x16x32_bf16 v[52:55], v[182:185], v[174:177], v[52:55]
	v_mfma_f32_16x16x32_bf16 v[16:19], v[182:185], v[178:181], v[16:19]
	s_waitcnt lgkmcnt(4)
	v_mfma_f32_16x16x32_bf16 v[48:51], v[186:189], v[174:177], v[48:51]
	v_mfma_f32_16x16x32_bf16 v[12:15], v[186:189], v[178:181], v[12:15]
	s_waitcnt lgkmcnt(3)
	v_mfma_f32_16x16x32_bf16 v[44:47], v[190:193], v[174:177], v[44:47]
	v_mfma_f32_16x16x32_bf16 v[8:11], v[190:193], v[178:181], v[8:11]
	s_waitcnt lgkmcnt(2)
	v_mfma_f32_16x16x32_bf16 v[40:43], v[194:197], v[174:177], v[40:43]
	v_mfma_f32_16x16x32_bf16 v[4:7], v[194:197], v[178:181], v[4:7]
	s_waitcnt lgkmcnt(1)
	v_mfma_f32_16x16x32_bf16 v[36:39], v[198:201], v[174:177], v[36:39]
	v_mfma_f32_16x16x32_bf16 v[0:3], v[198:201], v[178:181], v[0:3]
	s_waitcnt lgkmcnt(0)
	v_mfma_f32_16x16x32_bf16 v[32:35], v[202:205], v[174:177], v[32:35]
	v_mfma_f32_16x16x32_bf16 v[20:23], v[202:205], v[178:181], v[20:23]
	s_cbranch_scc0 .LBB0_1006
	v_add_u32_e32 v138, s36, v80
	v_add_u32_e32 v126, v138, v81
	s_waitcnt vmcnt(0)
	s_barrier
	ds_read_b128 v[74:77], v126 offset:16384
	v_add3_u32 v102, s36, v81, v82
	ds_read_b128 v[94:97], v102
	ds_read_b128 v[98:101], v126 offset:18432
	ds_read_b128 v[102:105], v102 offset:2048
	ds_read_b128 v[106:109], v126 offset:20480
	ds_read_b128 v[110:113], v126 offset:22528
	ds_read_b128 v[114:117], v126 offset:24576
	ds_read_b128 v[118:121], v126 offset:26624
	v_add3_u32 v134, s36, v83, v82
	v_add_u32_e32 v142, v138, v83
	ds_read_b128 v[122:125], v126 offset:28672
	ds_read_b128 v[126:129], v126 offset:30720
	ds_read_b128 v[130:133], v134
	ds_read_b128 v[134:137], v134 offset:2048
	ds_read_b128 v[138:141], v142 offset:16384
	ds_read_b128 v[146:149], v142 offset:18432
	s_waitcnt lgkmcnt(11)
	v_mfma_f32_16x16x32_bf16 v[56:59], v[98:101], v[94:97], v[56:59]
	s_lshl_b32 s36, s34, 7
	s_lshl_b32 s26, s33, 7
	s_ashr_i32 s27, s26, 31
	v_mfma_f32_16x16x32_bf16 v[60:63], v[74:77], v[94:97], v[60:63]
	s_lshl_b64 s[26:27], s[26:27], 1
	s_add_i32 s31, s31, s28
	s_cmpk_gt_i32 s31, 0x107f
	s_waitcnt lgkmcnt(0)
	v_mfma_f32_16x16x32_bf16 v[56:59], v[146:149], v[130:133], v[56:59]
	v_mfma_f32_16x16x32_bf16 v[48:51], v[110:113], v[94:97], v[48:51]
	v_mfma_f32_16x16x32_bf16 v[52:55], v[106:109], v[94:97], v[52:55]
	s_nop 5
	v_max_f32_e32 v56, v56, v56
	v_max_f32_e32 v57, v57, v57
	v_max_f32_e32 v56, 0, v56
	v_mfma_f32_16x16x32_bf16 v[44:47], v[114:117], v[94:97], v[44:47]
	v_max_f32_e32 v57, 0, v57
	v_max_f32_e32 v59, v59, v59
	v_max_f32_e32 v59, 0, v59
	v_mfma_f32_16x16x32_bf16 v[40:43], v[118:121], v[94:97], v[40:43]
	v_mfma_f32_16x16x32_bf16 v[36:39], v[122:125], v[94:97], v[36:39]
	v_mfma_f32_16x16x32_bf16 v[32:35], v[126:129], v[94:97], v[32:35]
	ds_read_b128 v[94:97], v142 offset:20480
	ds_read_b128 v[150:153], v142 offset:22528
	ds_read_b128 v[154:157], v142 offset:24576
	ds_read_b128 v[158:161], v142 offset:26624
	v_mfma_f32_16x16x32_bf16 v[60:63], v[138:141], v[130:133], v[60:63]
	s_waitcnt lgkmcnt(2)
	v_mfma_f32_16x16x32_bf16 v[48:51], v[150:153], v[130:133], v[48:51]
	v_mfma_f32_16x16x32_bf16 v[16:19], v[106:109], v[102:105], v[16:19]
	v_mul_f32_e64 v106, v56, v56
	v_mul_f32_e64 v107, v57, v57
	v_max_f32_e32 v57, v58, v58
	s_nop 1
	v_max_f32_e32 v60, v60, v60
	v_mfma_f32_16x16x32_bf16 v[24:27], v[98:101], v[102:105], v[24:27]
	v_add_u32_e32 v100, s36, v79
	v_mov_b64_e32 v[98:99], s[0:1]
	v_max_f32_e32 v61, v61, v61
	v_max_f32_e32 v56, v62, v62
	v_max_f32_e32 v58, 0, v57
	v_max_f32_e32 v57, v63, v63
	v_mad_i64_i32 v[100:101], s[34:35], v100, s30, v[98:99]
	v_max_f32_e32 v60, 0, v60
	v_max_f32_e32 v61, 0, v61
	v_max_f32_e32 v56, 0, v56
	v_max_f32_e32 v57, 0, v57
	v_mfma_f32_16x16x32_bf16 v[52:55], v[94:97], v[130:133], v[52:55]
	v_lshl_add_u64 v[100:101], v[100:101], 0, s[26:27]
	v_pk_mul_f32 v[60:61], v[60:61], v[60:61]
	v_pk_mul_f32 v[62:63], v[56:57], v[56:57]
	v_mfma_f32_16x16x32_bf16 v[28:31], v[74:77], v[102:105], v[28:31]
	v_max_f32_e32 v48, v48, v48
	v_max_f32_e32 v49, v49, v49
	ds_read_b128 v[74:77], v142 offset:28672
	ds_read_b128 v[162:165], v142 offset:30720
	v_mfma_f32_16x16x32_bf16 v[12:15], v[110:113], v[102:105], v[12:15]
	v_lshl_add_u64 v[100:101], v[100:101], 0, v[64:65]
	v_cvt_pk_bf16_f32 v56, v60, v61
	v_cvt_pk_bf16_f32 v57, v62, v63
	v_mfma_f32_16x16x32_bf16 v[8:11], v[114:117], v[102:105], v[8:11]
	v_max_f32_e32 v48, 0, v48
	v_max_f32_e32 v49, 0, v49
	v_max_f32_e32 v52, v52, v52
	v_mfma_f32_16x16x32_bf16 v[4:7], v[118:121], v[102:105], v[4:7]
	v_max_f32_e32 v53, v53, v53
	v_max_f32_e32 v51, v51, v51
	v_max_f32_e32 v52, 0, v52
	v_mfma_f32_16x16x32_bf16 v[0:3], v[122:125], v[102:105], v[0:3]
	v_max_f32_e32 v53, 0, v53
	v_max_f32_e32 v51, 0, v51
	v_pk_mul_f32 v[52:53], v[52:53], v[52:53]
	v_mfma_f32_16x16x32_bf16 v[20:23], v[126:129], v[102:105], v[20:23]
	v_mul_f32_e64 v102, v58, v58
	v_mul_f32_e64 v103, v59, v59
	v_cvt_pk_bf16_f32 v58, v106, v107
	v_cvt_pk_bf16_f32 v59, v102, v103
	s_waitcnt lgkmcnt(2)
	v_mfma_f32_16x16x32_bf16 v[40:43], v[158:161], v[130:133], v[40:43]
	global_store_dwordx4 v[100:101], v[56:59], off
	s_nop 1
	v_pk_mul_f32 v[56:57], v[48:49], v[48:49]
	v_max_f32_e32 v49, v50, v50
	v_max_f32_e32 v48, v54, v54
	v_max_f32_e32 v50, 0, v49
	v_max_f32_e32 v49, v55, v55
	v_mfma_f32_16x16x32_bf16 v[44:47], v[154:157], v[130:133], v[44:47]
	v_max_f32_e32 v48, 0, v48
	v_max_f32_e32 v49, 0, v49
	v_pk_mul_f32 v[54:55], v[48:49], v[48:49]
	v_pk_mul_f32 v[58:59], v[50:51], v[50:51]
	v_max_f32_e32 v40, v40, v40
	v_max_f32_e32 v41, v41, v41
	s_waitcnt lgkmcnt(0)
	v_mfma_f32_16x16x32_bf16 v[32:35], v[162:165], v[130:133], v[32:35]
	v_cvt_pk_bf16_f32 v48, v52, v53
	v_cvt_pk_bf16_f32 v49, v54, v55
	v_cvt_pk_bf16_f32 v50, v56, v57
	v_cvt_pk_bf16_f32 v51, v58, v59
	v_max_f32_e32 v40, 0, v40
	v_max_f32_e32 v41, 0, v41
	global_store_dwordx4 v[100:101], v[48:51], off offset:64
	v_max_f32_e32 v44, v44, v44
	v_max_f32_e32 v45, v45, v45
	v_pk_mul_f32 v[48:49], v[40:41], v[40:41]
	v_max_f32_e32 v41, v42, v42
	v_max_f32_e32 v40, v46, v46
	v_max_f32_e32 v42, 0, v41
	v_max_f32_e32 v41, v47, v47
	v_max_f32_e32 v43, v43, v43
	v_mfma_f32_16x16x32_bf16 v[36:39], v[74:77], v[130:133], v[36:39]
	v_max_f32_e32 v44, 0, v44
	v_max_f32_e32 v45, 0, v45
	v_max_f32_e32 v40, 0, v40
	v_max_f32_e32 v41, 0, v41
	v_max_f32_e32 v43, 0, v43
	v_pk_mul_f32 v[44:45], v[44:45], v[44:45]
	v_pk_mul_f32 v[46:47], v[40:41], v[40:41]
	v_pk_mul_f32 v[50:51], v[42:43], v[42:43]
	v_max_f32_e32 v32, v32, v32
	v_max_f32_e32 v33, v33, v33
	v_mfma_f32_16x16x32_bf16 v[24:27], v[146:149], v[134:137], v[24:27]
	v_cvt_pk_bf16_f32 v40, v44, v45
	v_cvt_pk_bf16_f32 v41, v46, v47
	v_cvt_pk_bf16_f32 v42, v48, v49
	v_cvt_pk_bf16_f32 v43, v50, v51
	v_max_f32_e32 v32, 0, v32
	v_max_f32_e32 v33, 0, v33
	global_store_dwordx4 v[100:101], v[40:43], off offset:128
	v_max_f32_e32 v36, v36, v36
	v_max_f32_e32 v37, v37, v37
	v_pk_mul_f32 v[40:41], v[32:33], v[32:33]
	v_max_f32_e32 v33, v34, v34
	v_max_f32_e32 v32, v38, v38
	v_max_f32_e32 v34, 0, v33
	v_max_f32_e32 v33, v39, v39
	v_max_f32_e32 v35, v35, v35
	v_mfma_f32_16x16x32_bf16 v[28:31], v[138:141], v[134:137], v[28:31]
	v_max_f32_e32 v36, 0, v36
	v_max_f32_e32 v37, 0, v37
	v_max_f32_e32 v32, 0, v32
	v_max_f32_e32 v33, 0, v33
	v_max_f32_e32 v35, 0, v35
	v_pk_mul_f32 v[36:37], v[36:37], v[36:37]
	v_pk_mul_f32 v[38:39], v[32:33], v[32:33]
	v_pk_mul_f32 v[42:43], v[34:35], v[34:35]
	v_max_f32_e32 v24, v24, v24
	v_max_f32_e32 v25, v25, v25
	v_mfma_f32_16x16x32_bf16 v[12:15], v[150:153], v[134:137], v[12:15]
	v_cvt_pk_bf16_f32 v32, v36, v37
	v_cvt_pk_bf16_f32 v33, v38, v39
	v_cvt_pk_bf16_f32 v34, v40, v41
	v_cvt_pk_bf16_f32 v35, v42, v43
	v_max_f32_e32 v24, 0, v24
	v_max_f32_e32 v25, 0, v25
	global_store_dwordx4 v[100:101], v[32:35], off offset:192
	v_max_f32_e32 v28, v28, v28
	v_max_f32_e32 v29, v29, v29
	v_pk_mul_f32 v[34:35], v[24:25], v[24:25]
	v_max_f32_e32 v25, v26, v26
	v_add_u32_e32 v32, s36, v84
	v_max_f32_e32 v24, v30, v30
	v_max_f32_e32 v26, 0, v25
	v_max_f32_e32 v25, v31, v31
	v_max_f32_e32 v27, v27, v27
	v_mfma_f32_16x16x32_bf16 v[16:19], v[94:97], v[134:137], v[16:19]
	v_mad_i64_i32 v[32:33], s[34:35], v32, s30, v[98:99]
	v_max_f32_e32 v28, 0, v28
	v_max_f32_e32 v29, 0, v29
	v_max_f32_e32 v24, 0, v24
	v_max_f32_e32 v25, 0, v25
	v_max_f32_e32 v27, 0, v27
	v_lshl_add_u64 v[32:33], v[32:33], 0, s[26:27]
	v_pk_mul_f32 v[28:29], v[28:29], v[28:29]
	v_pk_mul_f32 v[30:31], v[24:25], v[24:25]
	v_pk_mul_f32 v[36:37], v[26:27], v[26:27]
	v_max_f32_e32 v12, v12, v12
	v_max_f32_e32 v13, v13, v13
	v_mfma_f32_16x16x32_bf16 v[4:7], v[158:161], v[134:137], v[4:7]
	v_lshl_add_u64 v[32:33], v[32:33], 0, v[64:65]
	v_cvt_pk_bf16_f32 v24, v28, v29
	v_cvt_pk_bf16_f32 v25, v30, v31
	v_cvt_pk_bf16_f32 v26, v34, v35
	v_cvt_pk_bf16_f32 v27, v36, v37
	v_max_f32_e32 v12, 0, v12
	v_max_f32_e32 v13, 0, v13
	global_store_dwordx4 v[32:33], v[24:27], off
	v_max_f32_e32 v16, v16, v16
	v_max_f32_e32 v17, v17, v17
	v_pk_mul_f32 v[24:25], v[12:13], v[12:13]
	v_max_f32_e32 v13, v14, v14
	v_max_f32_e32 v12, v18, v18
	v_max_f32_e32 v14, 0, v13
	v_max_f32_e32 v13, v19, v19
	v_max_f32_e32 v15, v15, v15
	v_mfma_f32_16x16x32_bf16 v[8:11], v[154:157], v[134:137], v[8:11]
	v_max_f32_e32 v16, 0, v16
	v_max_f32_e32 v17, 0, v17
	v_max_f32_e32 v12, 0, v12
	v_max_f32_e32 v13, 0, v13
	v_max_f32_e32 v15, 0, v15
	v_pk_mul_f32 v[16:17], v[16:17], v[16:17]
	v_pk_mul_f32 v[18:19], v[12:13], v[12:13]
	v_pk_mul_f32 v[26:27], v[14:15], v[14:15]
	v_max_f32_e32 v4, v4, v4
	v_max_f32_e32 v5, v5, v5
	v_cvt_pk_bf16_f32 v12, v16, v17
	v_cvt_pk_bf16_f32 v13, v18, v19
	v_cvt_pk_bf16_f32 v14, v24, v25
	v_cvt_pk_bf16_f32 v15, v26, v27
	v_max_f32_e32 v4, 0, v4
	v_max_f32_e32 v5, 0, v5
	global_store_dwordx4 v[32:33], v[12:15], off offset:64
	v_mfma_f32_16x16x32_bf16 v[0:3], v[74:77], v[134:137], v[0:3]
	v_max_f32_e32 v8, v8, v8
	v_pk_mul_f32 v[12:13], v[4:5], v[4:5]
	v_max_f32_e32 v5, v6, v6
	v_mfma_f32_16x16x32_bf16 v[20:23], v[162:165], v[134:137], v[20:23]
	v_max_f32_e32 v9, v9, v9
	v_max_f32_e32 v4, v10, v10
	v_max_f32_e32 v6, 0, v5
	v_max_f32_e32 v5, v11, v11
	v_max_f32_e32 v7, v7, v7
	v_max_f32_e32 v8, 0, v8
	v_max_f32_e32 v9, 0, v9
	v_max_f32_e32 v4, 0, v4
	v_max_f32_e32 v5, 0, v5
	v_max_f32_e32 v7, 0, v7
	v_pk_mul_f32 v[8:9], v[8:9], v[8:9]
	v_pk_mul_f32 v[10:11], v[4:5], v[4:5]
	v_pk_mul_f32 v[14:15], v[6:7], v[6:7]
	v_cvt_pk_bf16_f32 v4, v8, v9
	v_cvt_pk_bf16_f32 v5, v10, v11
	v_cvt_pk_bf16_f32 v6, v12, v13
	v_cvt_pk_bf16_f32 v7, v14, v15
	global_store_dwordx4 v[32:33], v[4:7], off offset:128
	v_max_f32_e32 v0, v0, v0
	v_max_f32_e32 v1, v1, v1
	v_max_f32_e32 v4, v20, v20
	v_max_f32_e32 v5, v21, v21
	v_max_f32_e32 v2, v2, v2
	v_max_f32_e32 v6, v22, v22
	v_max_f32_e32 v3, v3, v3
	v_max_f32_e32 v7, v23, v23
	v_max_f32_e32 v0, 0, v0
	v_max_f32_e32 v4, 0, v4
	v_max_f32_e32 v1, 0, v1
	v_max_f32_e32 v5, 0, v5
	v_max_f32_e32 v2, 0, v2
	v_max_f32_e32 v6, 0, v6
	v_max_f32_e32 v3, 0, v3
	v_max_f32_e32 v7, 0, v7
	v_pk_mul_f32 v[0:1], v[0:1], v[0:1]
	v_pk_mul_f32 v[4:5], v[4:5], v[4:5]
	v_pk_mul_f32 v[2:3], v[2:3], v[2:3]
	v_pk_mul_f32 v[6:7], v[6:7], v[6:7]
	v_cvt_pk_bf16_f32 v0, v0, v1
	v_cvt_pk_bf16_f32 v1, v2, v3
	v_cvt_pk_bf16_f32 v2, v4, v5
	v_cvt_pk_bf16_f32 v3, v6, v7
	global_store_dwordx4 v[32:33], v[0:3], off offset:192
	s_cbranch_scc0 .LBB0_1005

.LBB0_1071:
	s_add_i32 s45, s43, 0x8000
	s_and_b32 s44, s45, 0x8000
	s_add_i32 s44, s44, 0
	s_add_u32 s86, s44, s87
	s_mov_b32 m0, s86
	s_waitcnt vmcnt(0) lgkmcnt(0)
	s_barrier
	s_and_b32 s43, s43, 0x8000
	s_add_i32 s43, s43, 0
	v_add3_u32 v169, s43, v84, v89
	v_add3_u32 v210, s43, v89, v90
	v_add3_u32 v211, s43, v84, v91
	v_add3_u32 v212, s43, v90, v91
	global_load_lds_dwordx4 v244, s[96:97]
	s_add_u32 m0, s86, 0x4000
	ds_read_b128 v[106:109], v210
	global_load_lds_dwordx4 v245, s[88:89]
	s_add_u32 m0, s86, 0x1000
	ds_read_b128 v[76:79], v169 offset:16384
	global_load_lds_dwordx4 v246, s[96:97]
	s_add_u32 m0, s86, 0x5000
	ds_read_b128 v[102:105], v169 offset:18432
	global_load_lds_dwordx4 v247, s[88:89]
	s_add_u32 m0, s86, 0x2000
	ds_read_b128 v[110:113], v210 offset:2048
	global_load_lds_dwordx4 v248, s[96:97]
	s_add_u32 m0, s86, 0x6000
	ds_read_b128 v[114:117], v169 offset:20480
	global_load_lds_dwordx4 v249, s[88:89]
	s_add_u32 m0, s86, 0x3000
	ds_read_b128 v[118:121], v169 offset:22528
	global_load_lds_dwordx4 v250, s[96:97]
	s_add_u32 m0, s86, 0x7000
	ds_read_b128 v[122:125], v169 offset:24576
	global_load_lds_dwordx4 v251, s[88:89]
	s_add_u32 s96, s96, 0x80
	s_addc_u32 s97, s97, 0
	s_add_u32 s88, s88, 0x80
	s_addc_u32 s89, s89, 0
	ds_read_b128 v[126:129], v169 offset:26624
	ds_read_b128 v[130:133], v169 offset:28672
	ds_read_b128 v[134:137], v169 offset:30720
	ds_read_b128 v[178:181], v212
	ds_read_b128 v[170:173], v211 offset:16384
	ds_read_b128 v[174:177], v211 offset:18432
	ds_read_b128 v[182:185], v212 offset:2048
	ds_read_b128 v[186:189], v211 offset:20480
	ds_read_b128 v[190:193], v211 offset:22528
	ds_read_b128 v[194:197], v211 offset:24576
	ds_read_b128 v[198:201], v211 offset:26624
	ds_read_b128 v[202:205], v211 offset:28672
	ds_read_b128 v[206:209], v211 offset:30720
	s_add_u32 s34, s34, 0x80
	s_addc_u32 s35, s35, 0
	s_cmpk_eq_i32 s34, 0x1f80
	s_mov_b32 s43, s45
	s_waitcnt lgkmcnt(15)
	v_mfma_f32_16x16x32_bf16 v[60:63], v[76:79], v[106:109], v[60:63]
	v_mfma_f32_16x16x32_bf16 v[56:59], v[102:105], v[106:109], v[56:59]
	v_mfma_f32_16x16x32_bf16 v[24:27], v[76:79], v[110:113], v[24:27]
	v_mfma_f32_16x16x32_bf16 v[20:23], v[102:105], v[110:113], v[20:23]
	v_mfma_f32_16x16x32_bf16 v[52:55], v[114:117], v[106:109], v[52:55]
	v_mfma_f32_16x16x32_bf16 v[16:19], v[114:117], v[110:113], v[16:19]
	s_waitcnt lgkmcnt(14)
	v_mfma_f32_16x16x32_bf16 v[48:51], v[118:121], v[106:109], v[48:51]
	v_mfma_f32_16x16x32_bf16 v[12:15], v[118:121], v[110:113], v[12:15]
	s_waitcnt lgkmcnt(13)
	v_mfma_f32_16x16x32_bf16 v[44:47], v[122:125], v[106:109], v[44:47]
	v_mfma_f32_16x16x32_bf16 v[8:11], v[122:125], v[110:113], v[8:11]
	s_waitcnt lgkmcnt(12)
	v_mfma_f32_16x16x32_bf16 v[40:43], v[126:129], v[106:109], v[40:43]
	v_mfma_f32_16x16x32_bf16 v[4:7], v[126:129], v[110:113], v[4:7]
	s_waitcnt lgkmcnt(11)
	v_mfma_f32_16x16x32_bf16 v[32:35], v[130:133], v[106:109], v[32:35]
	v_mfma_f32_16x16x32_bf16 v[0:3], v[130:133], v[110:113], v[0:3]
	s_waitcnt lgkmcnt(10)
	v_mfma_f32_16x16x32_bf16 v[28:31], v[134:137], v[106:109], v[28:31]
	v_mfma_f32_16x16x32_bf16 v[36:39], v[134:137], v[110:113], v[36:39]
	s_waitcnt lgkmcnt(8)
	v_mfma_f32_16x16x32_bf16 v[60:63], v[170:173], v[178:181], v[60:63]
	s_waitcnt lgkmcnt(7)
	v_mfma_f32_16x16x32_bf16 v[56:59], v[174:177], v[178:181], v[56:59]
	s_waitcnt lgkmcnt(6)
	v_mfma_f32_16x16x32_bf16 v[24:27], v[170:173], v[182:185], v[24:27]
	v_mfma_f32_16x16x32_bf16 v[20:23], v[174:177], v[182:185], v[20:23]
	s_waitcnt lgkmcnt(5)
	v_mfma_f32_16x16x32_bf16 v[52:55], v[186:189], v[178:181], v[52:55]
	v_mfma_f32_16x16x32_bf16 v[16:19], v[186:189], v[182:185], v[16:19]
	s_waitcnt lgkmcnt(4)
	v_mfma_f32_16x16x32_bf16 v[48:51], v[190:193], v[178:181], v[48:51]
	v_mfma_f32_16x16x32_bf16 v[12:15], v[190:193], v[182:185], v[12:15]
	s_waitcnt lgkmcnt(3)
	v_mfma_f32_16x16x32_bf16 v[44:47], v[194:197], v[178:181], v[44:47]
	v_mfma_f32_16x16x32_bf16 v[8:11], v[194:197], v[182:185], v[8:11]
	s_waitcnt lgkmcnt(2)
	v_mfma_f32_16x16x32_bf16 v[40:43], v[198:201], v[178:181], v[40:43]
	v_mfma_f32_16x16x32_bf16 v[4:7], v[198:201], v[182:185], v[4:7]
	s_waitcnt lgkmcnt(1)
	v_mfma_f32_16x16x32_bf16 v[32:35], v[202:205], v[178:181], v[32:35]
	v_mfma_f32_16x16x32_bf16 v[0:3], v[202:205], v[182:185], v[0:3]
	s_waitcnt lgkmcnt(0)
	v_mfma_f32_16x16x32_bf16 v[28:31], v[206:209], v[178:181], v[28:31]
	v_mfma_f32_16x16x32_bf16 v[36:39], v[206:209], v[182:185], v[36:39]
	s_cbranch_scc0 .LBB0_1071
	v_add_u32_e32 v80, s44, v84
	v_add_u32_e32 v81, v80, v89
	v_add3_u32 v106, s44, v89, v90
	s_waitcnt vmcnt(0)
	s_barrier
	ds_read_b128 v[72:75], v81 offset:16384
	ds_read_b128 v[76:79], v81 offset:18432
	ds_read_b128 v[102:105], v106
	ds_read_b128 v[106:109], v106 offset:2048
	ds_read_b128 v[110:113], v81 offset:20480
	ds_read_b128 v[114:117], v81 offset:22528
	ds_read_b128 v[118:121], v81 offset:24576
	ds_read_b128 v[122:125], v81 offset:26624
	ds_read_b128 v[126:129], v81 offset:28672
	ds_read_b128 v[130:133], v81 offset:30720
	v_add_u32_e32 v80, v80, v91
	s_waitcnt lgkmcnt(7)
	v_mfma_f32_16x16x32_bf16 v[60:63], v[72:75], v[102:105], v[60:63]
	s_lshl_b32 s42, s42, 7
	v_mfma_f32_16x16x32_bf16 v[56:59], v[76:79], v[102:105], v[56:59]
	s_waitcnt lgkmcnt(4)
	v_mfma_f32_16x16x32_bf16 v[48:51], v[114:117], v[102:105], v[48:51]
	s_waitcnt lgkmcnt(3)
	v_mfma_f32_16x16x32_bf16 v[44:47], v[118:121], v[102:105], v[44:47]
	s_waitcnt lgkmcnt(2)
	v_mfma_f32_16x16x32_bf16 v[40:43], v[122:125], v[102:105], v[40:43]
	s_waitcnt lgkmcnt(1)
	v_mfma_f32_16x16x32_bf16 v[32:35], v[126:129], v[102:105], v[32:35]
	s_waitcnt lgkmcnt(0)
	v_mfma_f32_16x16x32_bf16 v[28:31], v[130:133], v[102:105], v[28:31]
	v_mfma_f32_16x16x32_bf16 v[24:27], v[72:75], v[106:109], v[24:27]
	ds_read_b128 v[72:75], v80 offset:16384
	v_mfma_f32_16x16x32_bf16 v[52:55], v[110:113], v[102:105], v[52:55]
	v_mfma_f32_16x16x32_bf16 v[20:23], v[76:79], v[106:109], v[20:23]
	v_mfma_f32_16x16x32_bf16 v[16:19], v[110:113], v[106:109], v[16:19]
	v_mfma_f32_16x16x32_bf16 v[12:15], v[114:117], v[106:109], v[12:15]
	v_mfma_f32_16x16x32_bf16 v[8:11], v[118:121], v[106:109], v[8:11]
	v_mfma_f32_16x16x32_bf16 v[4:7], v[122:125], v[106:109], v[4:7]
	v_mfma_f32_16x16x32_bf16 v[0:3], v[126:129], v[106:109], v[0:3]
	v_mfma_f32_16x16x32_bf16 v[102:105], v[130:133], v[106:109], v[36:39]
	s_nop 2
	v_add3_u32 v36, s44, v91, v90
	ds_read_b128 v[76:79], v80 offset:18432
	ds_read_b128 v[106:109], v36
	ds_read_b128 v[110:113], v36 offset:2048
	ds_read_b128 v[130:133], v80 offset:28672
	ds_read_b128 v[134:137], v80 offset:30720
	ds_read_b128 v[114:117], v80 offset:20480
	ds_read_b128 v[118:121], v80 offset:22528
	ds_read_b128 v[122:125], v80 offset:24576
	ds_read_b128 v[126:129], v80 offset:26624
	s_waitcnt lgkmcnt(7)
	v_mfma_f32_16x16x32_bf16 v[60:63], v[72:75], v[106:109], v[60:63]
	s_waitcnt lgkmcnt(5)
	v_mfma_f32_16x16x32_bf16 v[36:39], v[130:133], v[106:109], v[32:35]
	s_waitcnt lgkmcnt(4)
	v_mfma_f32_16x16x32_bf16 v[32:35], v[134:137], v[106:109], v[28:31]
	v_mfma_f32_16x16x32_bf16 v[28:31], v[72:75], v[110:113], v[24:27]
	v_add_u32_e32 v72, s42, v85
	v_mul_hi_i32 v73, v72, s36
	v_mfma_f32_16x16x32_bf16 v[24:27], v[76:79], v[110:113], v[20:23]
	s_waitcnt lgkmcnt(3)
	v_mfma_f32_16x16x32_bf16 v[20:23], v[114:117], v[110:113], v[16:19]
	s_waitcnt lgkmcnt(2)
	v_mfma_f32_16x16x32_bf16 v[16:19], v[118:121], v[110:113], v[12:15]
	s_waitcnt lgkmcnt(1)
	v_mfma_f32_16x16x32_bf16 v[12:15], v[122:125], v[110:113], v[8:11]
	s_waitcnt lgkmcnt(0)
	v_mfma_f32_16x16x32_bf16 v[8:11], v[126:129], v[110:113], v[4:7]
	s_nop 2
	v_lshrrev_b32_e32 v4, 31, v73
	v_ashrrev_i32_e32 v5, 11, v73
	v_mfma_f32_16x16x32_bf16 v[56:59], v[76:79], v[106:109], v[56:59]
	v_add_u32_e32 v73, v5, v4
	v_mad_i32_i24 v78, v73, s37, v72
	v_lshlrev_b32_e32 v75, 13, v73
	v_mfma_f32_16x16x32_bf16 v[52:55], v[114:117], v[106:109], v[52:55]
	v_cmp_lt_i32_e32 vcc, s38, v78
	v_add3_u32 v74, v75, v78, s39
	v_mfma_f32_16x16x32_bf16 v[48:51], v[118:121], v[106:109], v[48:51]
	v_mfma_f32_16x16x32_bf16 v[44:47], v[122:125], v[106:109], v[44:47]
	v_mfma_f32_16x16x32_bf16 v[40:43], v[126:129], v[106:109], v[40:43]
	v_mfma_f32_16x16x32_bf16 v[4:7], v[130:133], v[110:113], v[0:3]
	v_mfma_f32_16x16x32_bf16 v[0:3], v[134:137], v[110:113], v[102:105]
	s_and_saveexec_b64 s[34:35], vcc
	s_xor_b64 s[34:35], exec, s[34:35]
	v_add3_u32 v72, v75, v78, s39
	s_or_saveexec_b64 s[34:35], s[34:35]
	v_mov_b64_e32 v[76:77], s[92:93]
	v_lshl_add_u32 v75, v73, 8, v78
	s_xor_b64 exec, exec, s[34:35]
	v_lshl_add_u32 v72, v73, 8, v78
	v_mov_b64_e32 v[76:77], s[6:7]
	s_or_b64 exec, exec, s[34:35]
	s_and_saveexec_b64 s[34:35], vcc
	s_xor_b64 s[34:35], exec, s[34:35]
	s_cbranch_execz .LBB0_1078
	v_mul_hi_i32_i24_e32 v79, 0x6000, v73
	v_mul_i32_i24_e32 v78, 0x6000, v73
	s_or_saveexec_b64 s[34:35], s[34:35]
	v_mov_b64_e32 v[80:81], s[92:93]
	s_xor_b64 exec, exec, s[34:35]
	s_cbranch_execnz .LBB0_1079
	s_branch .LBB0_1080

.LBB0_1091:
	s_add_i32 s48, s47, 0x8000
	s_and_b32 s8, s47, 0x8000
	s_and_b32 s47, s48, 0x8000
	s_add_i32 s49, s8, 0
	s_add_i32 s8, s47, 0
	s_add_u32 s71, s8, s75
	s_mov_b32 m0, s71
	s_waitcnt vmcnt(0) lgkmcnt(0)
	s_barrier
	v_add3_u32 v169, s49, v84, v87
	v_add3_u32 v210, s49, v87, v89
	v_add3_u32 v211, s49, v84, v90
	v_add3_u32 v212, s49, v89, v90
	global_load_lds_dwordx4 v236, s[84:85]
	s_add_u32 m0, s71, 0x4000
	ds_read_b128 v[104:107], v210
	global_load_lds_dwordx4 v237, s[72:73]
	s_add_u32 m0, s71, 0x1000
	ds_read_b128 v[68:71], v169 offset:16384
	global_load_lds_dwordx4 v238, s[84:85]
	s_add_u32 m0, s71, 0x5000
	ds_read_b128 v[100:103], v169 offset:18432
	global_load_lds_dwordx4 v239, s[72:73]
	s_add_u32 m0, s71, 0x2000
	ds_read_b128 v[108:111], v210 offset:2048
	global_load_lds_dwordx4 v240, s[84:85]
	s_add_u32 m0, s71, 0x6000
	ds_read_b128 v[112:115], v169 offset:20480
	global_load_lds_dwordx4 v241, s[72:73]
	s_add_u32 m0, s71, 0x3000
	ds_read_b128 v[116:119], v169 offset:22528
	global_load_lds_dwordx4 v242, s[84:85]
	s_add_u32 m0, s71, 0x7000
	ds_read_b128 v[120:123], v169 offset:24576
	global_load_lds_dwordx4 v243, s[72:73]
	s_add_u32 s84, s84, 0x80
	s_addc_u32 s85, s85, 0
	s_add_u32 s72, s72, 0x80
	s_addc_u32 s73, s73, 0
	ds_read_b128 v[124:127], v169 offset:26624
	ds_read_b128 v[128:131], v169 offset:28672
	ds_read_b128 v[132:135], v169 offset:30720
	ds_read_b128 v[178:181], v212
	ds_read_b128 v[170:173], v211 offset:16384
	ds_read_b128 v[174:177], v211 offset:18432
	ds_read_b128 v[182:185], v212 offset:2048
	ds_read_b128 v[186:189], v211 offset:20480
	ds_read_b128 v[190:193], v211 offset:22528
	ds_read_b128 v[194:197], v211 offset:24576
	ds_read_b128 v[198:201], v211 offset:26624
	ds_read_b128 v[202:205], v211 offset:28672
	ds_read_b128 v[206:209], v211 offset:30720
	s_add_u32 s36, s36, 0x80
	s_addc_u32 s37, s37, 0
	s_cmpk_eq_i32 s36, 0x780
	s_mov_b32 s47, s48
	s_waitcnt lgkmcnt(15)
	v_mfma_f32_16x16x32_bf16 v[60:63], v[68:71], v[104:107], v[60:63]
	v_mfma_f32_16x16x32_bf16 v[56:59], v[100:103], v[104:107], v[56:59]
	v_mfma_f32_16x16x32_bf16 v[28:31], v[68:71], v[108:111], v[28:31]
	v_mfma_f32_16x16x32_bf16 v[24:27], v[100:103], v[108:111], v[24:27]
	v_mfma_f32_16x16x32_bf16 v[52:55], v[112:115], v[104:107], v[52:55]
	v_mfma_f32_16x16x32_bf16 v[16:19], v[112:115], v[108:111], v[16:19]
	s_waitcnt lgkmcnt(14)
	v_mfma_f32_16x16x32_bf16 v[48:51], v[116:119], v[104:107], v[48:51]
	v_mfma_f32_16x16x32_bf16 v[12:15], v[116:119], v[108:111], v[12:15]
	s_waitcnt lgkmcnt(13)
	v_mfma_f32_16x16x32_bf16 v[44:47], v[120:123], v[104:107], v[44:47]
	v_mfma_f32_16x16x32_bf16 v[8:11], v[120:123], v[108:111], v[8:11]
	s_waitcnt lgkmcnt(12)
	v_mfma_f32_16x16x32_bf16 v[40:43], v[124:127], v[104:107], v[40:43]
	v_mfma_f32_16x16x32_bf16 v[4:7], v[124:127], v[108:111], v[4:7]
	s_waitcnt lgkmcnt(11)
	v_mfma_f32_16x16x32_bf16 v[36:39], v[128:131], v[104:107], v[36:39]
	v_mfma_f32_16x16x32_bf16 v[0:3], v[128:131], v[108:111], v[0:3]
	s_waitcnt lgkmcnt(10)
	v_mfma_f32_16x16x32_bf16 v[32:35], v[132:135], v[104:107], v[32:35]
	v_mfma_f32_16x16x32_bf16 v[20:23], v[132:135], v[108:111], v[20:23]
	s_waitcnt lgkmcnt(8)
	v_mfma_f32_16x16x32_bf16 v[60:63], v[170:173], v[178:181], v[60:63]
	s_waitcnt lgkmcnt(7)
	v_mfma_f32_16x16x32_bf16 v[56:59], v[174:177], v[178:181], v[56:59]
	s_waitcnt lgkmcnt(6)
	v_mfma_f32_16x16x32_bf16 v[28:31], v[170:173], v[182:185], v[28:31]
	v_mfma_f32_16x16x32_bf16 v[24:27], v[174:177], v[182:185], v[24:27]
	s_waitcnt lgkmcnt(5)
	v_mfma_f32_16x16x32_bf16 v[52:55], v[186:189], v[178:181], v[52:55]
	v_mfma_f32_16x16x32_bf16 v[16:19], v[186:189], v[182:185], v[16:19]
	s_waitcnt lgkmcnt(4)
	v_mfma_f32_16x16x32_bf16 v[48:51], v[190:193], v[178:181], v[48:51]
	v_mfma_f32_16x16x32_bf16 v[12:15], v[190:193], v[182:185], v[12:15]
	s_waitcnt lgkmcnt(3)
	v_mfma_f32_16x16x32_bf16 v[44:47], v[194:197], v[178:181], v[44:47]
	v_mfma_f32_16x16x32_bf16 v[8:11], v[194:197], v[182:185], v[8:11]
	s_waitcnt lgkmcnt(2)
	v_mfma_f32_16x16x32_bf16 v[40:43], v[198:201], v[178:181], v[40:43]
	v_mfma_f32_16x16x32_bf16 v[4:7], v[198:201], v[182:185], v[4:7]
	s_waitcnt lgkmcnt(1)
	v_mfma_f32_16x16x32_bf16 v[36:39], v[202:205], v[178:181], v[36:39]
	v_mfma_f32_16x16x32_bf16 v[0:3], v[202:205], v[182:185], v[0:3]
	s_waitcnt lgkmcnt(0)
	v_mfma_f32_16x16x32_bf16 v[32:35], v[206:209], v[178:181], v[32:35]
	v_mfma_f32_16x16x32_bf16 v[20:23], v[206:209], v[182:185], v[20:23]
	s_cbranch_scc0 .LBB0_1091
	v_lshl_add_u32 v99, s46, 7, v85
	v_mul_hi_i32 v64, v99, s39
	v_lshrrev_b32_e32 v65, 31, v64
	v_ashrrev_i32_e32 v64, 11, v64
	v_add_u32_e32 v64, v64, v65
	v_mad_i32_i24 v65, v64, s40, v99
	v_cmp_lt_i32_e32 vcc, s41, v65
	v_lshl_or_b32 v72, s45, 9, v86
	s_waitcnt vmcnt(0)
	v_cndmask_b32_e32 v64, 2, v64, vcc
	v_mul_hi_i32_i24_e32 v65, 0x6000, v64
	v_mul_i32_i24_e32 v64, 0x6000, v64
	v_lshl_add_u64 v[64:65], s[94:95], 0, v[64:65]
	v_lshl_add_u64 v[150:151], v[64:65], 0, s[34:35]
	v_lshl_add_u64 v[64:65], v[150:151], 0, v[72:73]
	s_barrier
	global_load_dwordx4 v[100:103], v[64:65], off
	v_add3_u32 v64, s8, v87, v89
	v_add_u32_e32 v68, s8, v84
	ds_read_b128 v[104:107], v64
	ds_read_b128 v[108:111], v64 offset:2048
	v_add3_u32 v65, s8, v90, v89
	v_add_u32_e32 v145, v68, v87
	ds_read_b128 v[112:115], v65
	ds_read_b128 v[64:67], v65 offset:2048
	v_add_u32_e32 v168, v68, v90
	ds_read_b128 v[116:119], v145 offset:16384
	ds_read_b128 v[120:123], v145 offset:18432
	ds_read_b128 v[124:127], v168 offset:16384
	ds_read_b128 v[68:71], v168 offset:18432
	v_mul_hi_i32 v128, v99, s38
	s_waitcnt lgkmcnt(3)
	v_mfma_f32_16x16x32_bf16 v[60:63], v[116:119], v[104:107], v[60:63]
	v_lshrrev_b32_e32 v129, 31, v128
	v_lshrrev_b32_e32 v128, 11, v128
	v_add_u32_e32 v128, v128, v129
	v_lshl_add_u32 v128, v128, 13, v99
	s_lshl_b32 s8, s44, 9
	v_ashrrev_i32_e32 v129, 31, v128
	s_waitcnt lgkmcnt(1)
	v_mfma_f32_16x16x32_bf16 v[60:63], v[124:127], v[112:115], v[60:63]
	v_lshl_add_u64 v[128:129], v[128:129], 0, s[8:9]
	v_lshlrev_b64 v[128:129], 12, v[128:129]
	v_lshl_add_u64 v[128:129], s[6:7], 0, v[128:129]
	v_mov_b32_e32 v153, v73
	v_or_b32_e32 v152, 16, v72
	v_lshl_add_u64 v[154:155], v[128:129], 0, v[72:73]
	v_lshl_add_u64 v[128:129], v[150:151], 0, v[152:153]
	v_mfma_f32_16x16x32_bf16 v[56:59], v[120:123], v[104:107], v[56:59]
	v_mov_b32_e32 v157, v73
	v_or_b32_e32 v156, 0x80, v72
	v_mov_b32_e32 v159, v73
	s_waitcnt lgkmcnt(0)
	v_mfma_f32_16x16x32_bf16 v[56:59], v[68:71], v[112:115], v[56:59]
	v_or_b32_e32 v158, 0x90, v72
	v_lshl_add_u64 v[136:137], v[150:151], 0, v[158:159]
	v_mov_b32_e32 v161, v73
	v_or_b32_e32 v160, 0x100, v72
	v_mov_b32_e32 v163, v73
	v_or_b32_e32 v162, 0x110, v72
	v_lshl_add_u64 v[146:147], v[150:151], 0, v[162:163]
	v_mov_b32_e32 v165, v73
	v_or_b32_e32 v164, 0x180, v72
	v_lshl_add_u64 v[166:167], v[150:151], 0, v[164:165]
	v_mfma_f32_16x16x32_bf16 v[28:31], v[116:119], v[108:111], v[28:31]
	v_or_b32_e32 v99, 16, v99
	s_add_i32 s43, s43, s33
	s_add_i32 s42, s42, s33
	v_mfma_f32_16x16x32_bf16 v[28:31], v[124:127], v[64:67], v[28:31]
	s_cmpk_gt_i32 s43, 0x7f
	s_waitcnt vmcnt(0)
	v_pk_mul_f32 v[62:63], v[62:63], v[102:103]
	v_pk_mul_f32 v[60:61], v[60:61], v[100:101]
	global_store_dwordx4 v[154:155], v[60:63], off
	global_load_dwordx4 v[60:63], v[128:129], off
	v_lshl_add_u64 v[100:101], v[150:151], 0, v[156:157]
	v_mfma_f32_16x16x32_bf16 v[24:27], v[120:123], v[108:111], v[24:27]
	s_waitcnt vmcnt(0)
	v_pk_mul_f32 v[58:59], v[58:59], v[62:63]
	v_pk_mul_f32 v[56:57], v[56:57], v[60:61]
	global_store_dwordx4 v[154:155], v[56:59], off offset:16
	global_load_dwordx4 v[56:59], v[100:101], off
	ds_read_b128 v[60:63], v145 offset:20480
	ds_read_b128 v[100:103], v168 offset:20480
	s_waitcnt lgkmcnt(1)
	v_mfma_f32_16x16x32_bf16 v[52:55], v[60:63], v[104:107], v[52:55]
	ds_read_b128 v[128:131], v145 offset:22528
	ds_read_b128 v[132:135], v168 offset:22528
	s_waitcnt lgkmcnt(2)
	v_mfma_f32_16x16x32_bf16 v[52:55], v[100:103], v[112:115], v[52:55]
	s_waitcnt lgkmcnt(1)
	v_mfma_f32_16x16x32_bf16 v[48:51], v[128:131], v[104:107], v[48:51]
	s_waitcnt vmcnt(0)
	s_nop 4
	v_pk_mul_f32 v[54:55], v[54:55], v[58:59]
	v_pk_mul_f32 v[52:53], v[52:53], v[56:57]
	global_store_dwordx4 v[154:155], v[52:55], off offset:128
	global_load_dwordx4 v[52:55], v[136:137], off
	s_waitcnt lgkmcnt(0)
	v_mfma_f32_16x16x32_bf16 v[48:51], v[132:135], v[112:115], v[48:51]
	v_lshl_add_u64 v[56:57], v[150:151], 0, v[160:161]
	v_mfma_f32_16x16x32_bf16 v[24:27], v[68:71], v[64:67], v[24:27]
	v_mfma_f32_16x16x32_bf16 v[16:19], v[60:63], v[108:111], v[16:19]
	s_waitcnt vmcnt(0)
	s_nop 3
	v_pk_mul_f32 v[50:51], v[50:51], v[54:55]
	v_pk_mul_f32 v[48:49], v[48:49], v[52:53]
	global_store_dwordx4 v[154:155], v[48:51], off offset:144
	global_load_dwordx4 v[48:51], v[56:57], off
	ds_read_b128 v[52:55], v145 offset:24576
	ds_read_b128 v[56:59], v168 offset:24576
	s_waitcnt lgkmcnt(1)
	v_mfma_f32_16x16x32_bf16 v[44:47], v[52:55], v[104:107], v[44:47]
	ds_read_b128 v[136:139], v145 offset:26624
	ds_read_b128 v[140:143], v168 offset:26624
	s_waitcnt lgkmcnt(2)
	v_mfma_f32_16x16x32_bf16 v[44:47], v[56:59], v[112:115], v[44:47]
	s_waitcnt lgkmcnt(1)
	v_mfma_f32_16x16x32_bf16 v[40:43], v[136:139], v[104:107], v[40:43]
	s_waitcnt vmcnt(0)
	s_nop 4
	v_pk_mul_f32 v[46:47], v[46:47], v[50:51]
	v_pk_mul_f32 v[44:45], v[44:45], v[48:49]
	global_store_dwordx4 v[154:155], v[44:47], off offset:256
	global_load_dwordx4 v[44:47], v[146:147], off
	s_waitcnt lgkmcnt(0)
	v_mfma_f32_16x16x32_bf16 v[40:43], v[140:143], v[112:115], v[40:43]
	ds_read_b128 v[48:51], v145 offset:28672
	ds_read_b128 v[146:149], v145 offset:30720
	s_waitcnt lgkmcnt(1)
	v_mfma_f32_16x16x32_bf16 v[36:39], v[48:51], v[104:107], v[36:39]
	s_waitcnt vmcnt(0)
	s_nop 2
	v_pk_mul_f32 v[42:43], v[42:43], v[46:47]
	v_pk_mul_f32 v[40:41], v[40:41], v[44:45]
	global_store_dwordx4 v[154:155], v[40:43], off offset:272
	global_load_dwordx4 v[40:43], v[166:167], off
	ds_read_b128 v[44:47], v168 offset:28672
	s_waitcnt lgkmcnt(1)
	v_mfma_f32_16x16x32_bf16 v[32:35], v[146:149], v[104:107], v[32:35]
	ds_read_b128 v[104:107], v168 offset:30720
	v_mov_b32_e32 v167, v73
	v_or_b32_e32 v166, 0x190, v72
	s_waitcnt lgkmcnt(1)
	v_mfma_f32_16x16x32_bf16 v[36:39], v[44:47], v[112:115], v[36:39]
	v_lshl_add_u64 v[116:117], v[150:151], 0, v[166:167]
	s_waitcnt vmcnt(0)
	s_nop 5
	v_pk_mul_f32 v[38:39], v[38:39], v[42:43]
	v_pk_mul_f32 v[36:37], v[36:37], v[40:41]
	global_store_dwordx4 v[154:155], v[36:39], off offset:384
	global_load_dwordx4 v[36:39], v[116:117], off
	v_mul_hi_i32 v40, v99, s39
	v_lshrrev_b32_e32 v41, 31, v40
	v_ashrrev_i32_e32 v40, 11, v40
	v_add_u32_e32 v40, v40, v41
	v_mad_i32_i24 v41, v40, s40, v99
	v_cmp_lt_i32_e32 vcc, s41, v41
	s_waitcnt lgkmcnt(0)
	v_mfma_f32_16x16x32_bf16 v[32:35], v[104:107], v[112:115], v[32:35]
	v_cndmask_b32_e32 v40, 2, v40, vcc
	v_mul_hi_i32_i24_e32 v41, 0x6000, v40
	v_mul_i32_i24_e32 v40, 0x6000, v40
	v_lshl_add_u64 v[40:41], s[94:95], 0, v[40:41]
	v_lshl_add_u64 v[40:41], v[40:41], 0, s[34:35]
	v_lshl_add_u64 v[42:43], v[40:41], 0, v[72:73]
	v_mfma_f32_16x16x32_bf16 v[16:19], v[100:103], v[64:67], v[16:19]
	s_waitcnt vmcnt(0)
	v_pk_mul_f32 v[34:35], v[34:35], v[38:39]
	v_pk_mul_f32 v[32:33], v[32:33], v[36:37]
	global_store_dwordx4 v[154:155], v[32:35], off offset:400
	global_load_dwordx4 v[32:35], v[42:43], off
	v_mul_hi_i32 v36, v99, s38
	v_lshrrev_b32_e32 v37, 31, v36
	v_lshrrev_b32_e32 v36, 11, v36
	v_add_u32_e32 v36, v36, v37
	v_lshl_add_u32 v36, v36, 13, v99
	v_ashrrev_i32_e32 v37, 31, v36
	v_lshl_add_u64 v[36:37], v[36:37], 0, s[8:9]
	v_lshlrev_b64 v[36:37], 12, v[36:37]
	v_lshl_add_u64 v[36:37], s[6:7], 0, v[36:37]
	v_lshl_add_u64 v[36:37], v[36:37], 0, v[72:73]
	v_lshl_add_u64 v[38:39], v[40:41], 0, v[152:153]
	v_mfma_f32_16x16x32_bf16 v[12:15], v[128:131], v[108:111], v[12:15]
	s_waitcnt vmcnt(0)
	v_pk_mul_f32 v[30:31], v[30:31], v[34:35]
	v_pk_mul_f32 v[28:29], v[28:29], v[32:33]
	global_store_dwordx4 v[36:37], v[28:31], off
	global_load_dwordx4 v[28:31], v[38:39], off
	v_lshl_add_u64 v[32:33], v[40:41], 0, v[156:157]
	v_mfma_f32_16x16x32_bf16 v[12:15], v[132:135], v[64:67], v[12:15]
	s_waitcnt vmcnt(0)
	v_pk_mul_f32 v[26:27], v[26:27], v[30:31]
	v_pk_mul_f32 v[24:25], v[24:25], v[28:29]
	global_store_dwordx4 v[36:37], v[24:27], off offset:16
	global_load_dwordx4 v[24:27], v[32:33], off
	v_lshl_add_u64 v[28:29], v[40:41], 0, v[158:159]
	v_mfma_f32_16x16x32_bf16 v[8:11], v[52:55], v[108:111], v[8:11]
	s_waitcnt vmcnt(0)
	v_pk_mul_f32 v[18:19], v[18:19], v[26:27]
	v_pk_mul_f32 v[16:17], v[16:17], v[24:25]
	global_store_dwordx4 v[36:37], v[16:19], off offset:128
	global_load_dwordx4 v[16:19], v[28:29], off
	v_lshl_add_u64 v[24:25], v[40:41], 0, v[160:161]
	v_mfma_f32_16x16x32_bf16 v[8:11], v[56:59], v[64:67], v[8:11]
	s_waitcnt vmcnt(0)
	v_pk_mul_f32 v[14:15], v[14:15], v[18:19]
	v_pk_mul_f32 v[12:13], v[12:13], v[16:17]
	global_store_dwordx4 v[36:37], v[12:15], off offset:144
	global_load_dwordx4 v[12:15], v[24:25], off
	v_lshl_add_u64 v[16:17], v[40:41], 0, v[162:163]
	v_mfma_f32_16x16x32_bf16 v[4:7], v[136:139], v[108:111], v[4:7]
	s_waitcnt vmcnt(0)
	v_pk_mul_f32 v[10:11], v[10:11], v[14:15]
	v_pk_mul_f32 v[8:9], v[8:9], v[12:13]
	global_store_dwordx4 v[36:37], v[8:11], off offset:256
	global_load_dwordx4 v[8:11], v[16:17], off
	v_mfma_f32_16x16x32_bf16 v[4:7], v[140:143], v[64:67], v[4:7]
	v_lshl_add_u64 v[12:13], v[40:41], 0, v[164:165]
	v_mfma_f32_16x16x32_bf16 v[0:3], v[48:51], v[108:111], v[0:3]
	v_mfma_f32_16x16x32_bf16 v[0:3], v[44:47], v[64:67], v[0:3]
	s_waitcnt vmcnt(0)
	s_nop 3
	v_pk_mul_f32 v[6:7], v[6:7], v[10:11]
	v_pk_mul_f32 v[4:5], v[4:5], v[8:9]
	global_store_dwordx4 v[36:37], v[4:7], off offset:272
	global_load_dwordx4 v[4:7], v[12:13], off
	v_lshl_add_u64 v[8:9], v[40:41], 0, v[166:167]
	v_mfma_f32_16x16x32_bf16 v[20:23], v[146:149], v[108:111], v[20:23]
	s_waitcnt vmcnt(0)
	v_pk_mul_f32 v[2:3], v[2:3], v[6:7]
	v_pk_mul_f32 v[0:1], v[0:1], v[4:5]
	global_store_dwordx4 v[36:37], v[0:3], off offset:384
	global_load_dwordx4 v[0:3], v[8:9], off
	v_mfma_f32_16x16x32_bf16 v[4:7], v[104:107], v[64:67], v[20:23]
	s_waitcnt vmcnt(0)
	s_nop 6
	v_pk_mul_f32 v[2:3], v[6:7], v[2:3]
	v_pk_mul_f32 v[0:1], v[4:5], v[0:1]
	global_store_dwordx4 v[36:37], v[0:3], off offset:400
	s_cbranch_scc0 .LBB0_1090

.LBB0_1217:
	s_add_i32 s41, s3, 0x8000
	s_and_b32 s40, s41, 0x8000
	s_add_i32 s40, s40, 0
	s_add_u32 s86, s40, s87
	s_mov_b32 m0, s86
	s_waitcnt vmcnt(0) lgkmcnt(0)
	s_barrier
	s_and_b32 s3, s3, 0x8000
	s_add_i32 s3, s3, 0
	v_add3_u32 v145, s3, v87, v88
	v_add3_u32 v186, s3, v88, v89
	v_add3_u32 v187, s3, v87, v90
	v_add3_u32 v188, s3, v89, v90
	global_load_lds_dwordx4 v244, s[96:97]
	s_add_u32 m0, s86, 0x4000
	ds_read_b128 v[112:115], v186
	global_load_lds_dwordx4 v245, s[88:89]
	s_add_u32 m0, s86, 0x1000
	ds_read_b128 v[104:107], v145 offset:16384
	global_load_lds_dwordx4 v246, s[96:97]
	s_add_u32 m0, s86, 0x5000
	ds_read_b128 v[108:111], v145 offset:18432
	global_load_lds_dwordx4 v247, s[88:89]
	s_add_u32 m0, s86, 0x2000
	ds_read_b128 v[116:119], v186 offset:2048
	global_load_lds_dwordx4 v248, s[96:97]
	s_add_u32 m0, s86, 0x6000
	ds_read_b128 v[120:123], v145 offset:20480
	global_load_lds_dwordx4 v249, s[88:89]
	s_add_u32 m0, s86, 0x3000
	ds_read_b128 v[124:127], v145 offset:22528
	global_load_lds_dwordx4 v250, s[96:97]
	s_add_u32 m0, s86, 0x7000
	ds_read_b128 v[128:131], v145 offset:24576
	global_load_lds_dwordx4 v251, s[88:89]
	s_add_u32 s96, s96, 0x80
	s_addc_u32 s97, s97, 0
	s_add_u32 s88, s88, 0x80
	s_addc_u32 s89, s89, 0
	ds_read_b128 v[132:135], v145 offset:26624
	ds_read_b128 v[136:139], v145 offset:28672
	ds_read_b128 v[140:143], v145 offset:30720
	ds_read_b128 v[154:157], v188
	ds_read_b128 v[146:149], v187 offset:16384
	ds_read_b128 v[150:153], v187 offset:18432
	ds_read_b128 v[158:161], v188 offset:2048
	ds_read_b128 v[162:165], v187 offset:20480
	ds_read_b128 v[166:169], v187 offset:22528
	ds_read_b128 v[170:173], v187 offset:24576
	ds_read_b128 v[174:177], v187 offset:26624
	ds_read_b128 v[178:181], v187 offset:28672
	ds_read_b128 v[182:185], v187 offset:30720
	s_add_u32 s0, s0, 0x80
	s_addc_u32 s1, s1, 0
	s_cmpk_eq_i32 s0, 0x780
	s_mov_b32 s3, s41
	s_waitcnt lgkmcnt(15)
	v_mfma_f32_16x16x32_bf16 v[60:63], v[104:107], v[112:115], v[60:63]
	v_mfma_f32_16x16x32_bf16 v[56:59], v[108:111], v[112:115], v[56:59]
	v_mfma_f32_16x16x32_bf16 v[24:27], v[104:107], v[116:119], v[24:27]
	v_mfma_f32_16x16x32_bf16 v[20:23], v[108:111], v[116:119], v[20:23]
	v_mfma_f32_16x16x32_bf16 v[52:55], v[120:123], v[112:115], v[52:55]
	v_mfma_f32_16x16x32_bf16 v[16:19], v[120:123], v[116:119], v[16:19]
	s_waitcnt lgkmcnt(14)
	v_mfma_f32_16x16x32_bf16 v[48:51], v[124:127], v[112:115], v[48:51]
	v_mfma_f32_16x16x32_bf16 v[12:15], v[124:127], v[116:119], v[12:15]
	s_waitcnt lgkmcnt(13)
	v_mfma_f32_16x16x32_bf16 v[44:47], v[128:131], v[112:115], v[44:47]
	v_mfma_f32_16x16x32_bf16 v[8:11], v[128:131], v[116:119], v[8:11]
	s_waitcnt lgkmcnt(12)
	v_mfma_f32_16x16x32_bf16 v[36:39], v[132:135], v[112:115], v[36:39]
	v_mfma_f32_16x16x32_bf16 v[4:7], v[132:135], v[116:119], v[4:7]
	s_waitcnt lgkmcnt(11)
	v_mfma_f32_16x16x32_bf16 v[32:35], v[136:139], v[112:115], v[32:35]
	v_mfma_f32_16x16x32_bf16 v[0:3], v[136:139], v[116:119], v[0:3]
	s_waitcnt lgkmcnt(10)
	v_mfma_f32_16x16x32_bf16 v[28:31], v[140:143], v[112:115], v[28:31]
	v_mfma_f32_16x16x32_bf16 v[40:43], v[140:143], v[116:119], v[40:43]
	s_waitcnt lgkmcnt(8)
	v_mfma_f32_16x16x32_bf16 v[60:63], v[146:149], v[154:157], v[60:63]
	s_waitcnt lgkmcnt(7)
	v_mfma_f32_16x16x32_bf16 v[56:59], v[150:153], v[154:157], v[56:59]
	s_waitcnt lgkmcnt(6)
	v_mfma_f32_16x16x32_bf16 v[24:27], v[146:149], v[158:161], v[24:27]
	v_mfma_f32_16x16x32_bf16 v[20:23], v[150:153], v[158:161], v[20:23]
	s_waitcnt lgkmcnt(5)
	v_mfma_f32_16x16x32_bf16 v[52:55], v[162:165], v[154:157], v[52:55]
	v_mfma_f32_16x16x32_bf16 v[16:19], v[162:165], v[158:161], v[16:19]
	s_waitcnt lgkmcnt(4)
	v_mfma_f32_16x16x32_bf16 v[48:51], v[166:169], v[154:157], v[48:51]
	v_mfma_f32_16x16x32_bf16 v[12:15], v[166:169], v[158:161], v[12:15]
	s_waitcnt lgkmcnt(3)
	v_mfma_f32_16x16x32_bf16 v[44:47], v[170:173], v[154:157], v[44:47]
	v_mfma_f32_16x16x32_bf16 v[8:11], v[170:173], v[158:161], v[8:11]
	s_waitcnt lgkmcnt(2)
	v_mfma_f32_16x16x32_bf16 v[36:39], v[174:177], v[154:157], v[36:39]
	v_mfma_f32_16x16x32_bf16 v[4:7], v[174:177], v[158:161], v[4:7]
	s_waitcnt lgkmcnt(1)
	v_mfma_f32_16x16x32_bf16 v[32:35], v[178:181], v[154:157], v[32:35]
	v_mfma_f32_16x16x32_bf16 v[0:3], v[178:181], v[158:161], v[0:3]
	s_waitcnt lgkmcnt(0)
	v_mfma_f32_16x16x32_bf16 v[28:31], v[182:185], v[154:157], v[28:31]
	v_mfma_f32_16x16x32_bf16 v[40:43], v[182:185], v[158:161], v[40:43]
	s_cbranch_scc0 .LBB0_1217
	v_add_u32_e32 v64, s40, v87
	v_add_u32_e32 v103, v64, v88
	v_add3_u32 v112, s40, v88, v89
	s_waitcnt vmcnt(0)
	s_barrier
	ds_read_b128 v[82:85], v103 offset:16384
	ds_read_b128 v[104:107], v103 offset:18432
	ds_read_b128 v[108:111], v112
	ds_read_b128 v[112:115], v112 offset:2048
	ds_read_b128 v[116:119], v103 offset:20480
	ds_read_b128 v[120:123], v103 offset:22528
	ds_read_b128 v[124:127], v103 offset:24576
	ds_read_b128 v[128:131], v103 offset:26624
	ds_read_b128 v[132:135], v103 offset:28672
	ds_read_b128 v[136:139], v103 offset:30720
	v_add_u32_e32 v64, v64, v90
	s_waitcnt lgkmcnt(7)
	v_mfma_f32_16x16x32_bf16 v[60:63], v[82:85], v[108:111], v[60:63]
	s_mul_hi_i32 s0, s2, 0x3e0f83e1
	s_lshr_b32 s1, s0, 31
	s_ashr_i32 s56, s0, 4
	v_mfma_f32_16x16x32_bf16 v[56:59], v[104:107], v[108:111], v[56:59]
	s_add_i32 s56, s56, s1
	s_cmp_gt_i32 s39, 11
	s_cselect_b64 s[0:1], -1, 0
	s_waitcnt lgkmcnt(4)
	v_mfma_f32_16x16x32_bf16 v[48:51], v[120:123], v[108:111], v[48:51]
	s_lshl_b32 s53, s2, 7
	s_cmp_lt_i32 s39, 12
	s_mul_i32 s54, s56, 0xffffdf00
	s_waitcnt lgkmcnt(3)
	v_mfma_f32_16x16x32_bf16 v[44:47], v[124:127], v[108:111], v[44:47]
	s_waitcnt lgkmcnt(2)
	v_mfma_f32_16x16x32_bf16 v[36:39], v[128:131], v[108:111], v[36:39]
	s_waitcnt lgkmcnt(1)
	v_mfma_f32_16x16x32_bf16 v[32:35], v[132:135], v[108:111], v[32:35]
	s_waitcnt lgkmcnt(0)
	v_mfma_f32_16x16x32_bf16 v[28:31], v[136:139], v[108:111], v[28:31]
	v_mfma_f32_16x16x32_bf16 v[24:27], v[82:85], v[112:115], v[24:27]
	ds_read_b128 v[82:85], v64 offset:16384
	v_mfma_f32_16x16x32_bf16 v[52:55], v[116:119], v[108:111], v[52:55]
	v_mfma_f32_16x16x32_bf16 v[20:23], v[104:107], v[112:115], v[20:23]
	v_mfma_f32_16x16x32_bf16 v[16:19], v[116:119], v[112:115], v[16:19]
	v_mfma_f32_16x16x32_bf16 v[12:15], v[120:123], v[112:115], v[12:15]
	v_mfma_f32_16x16x32_bf16 v[8:11], v[124:127], v[112:115], v[8:11]
	v_mfma_f32_16x16x32_bf16 v[4:7], v[128:131], v[112:115], v[4:7]
	v_mfma_f32_16x16x32_bf16 v[0:3], v[132:135], v[112:115], v[0:3]
	v_mfma_f32_16x16x32_bf16 v[104:107], v[136:139], v[112:115], v[40:43]
	s_nop 2
	v_add3_u32 v40, s40, v90, v89
	ds_read_b128 v[108:111], v64 offset:18432
	ds_read_b128 v[112:115], v40
	ds_read_b128 v[116:119], v40 offset:2048
	ds_read_b128 v[120:123], v64 offset:20480
	ds_read_b128 v[124:127], v64 offset:22528
	ds_read_b128 v[128:131], v64 offset:24576
	ds_read_b128 v[132:135], v64 offset:26624
	ds_read_b128 v[136:139], v64 offset:28672
	ds_read_b128 v[140:143], v64 offset:30720
	s_waitcnt lgkmcnt(7)
	v_mfma_f32_16x16x32_bf16 v[60:63], v[82:85], v[112:115], v[60:63]
	v_mfma_f32_16x16x32_bf16 v[56:59], v[108:111], v[112:115], v[56:59]
	s_waitcnt lgkmcnt(5)
	v_mfma_f32_16x16x32_bf16 v[52:55], v[120:123], v[112:115], v[52:55]
	s_waitcnt lgkmcnt(4)
	v_mfma_f32_16x16x32_bf16 v[48:51], v[124:127], v[112:115], v[48:51]
	s_waitcnt lgkmcnt(3)
	v_mfma_f32_16x16x32_bf16 v[44:47], v[128:131], v[112:115], v[44:47]
	s_waitcnt lgkmcnt(2)
	v_mfma_f32_16x16x32_bf16 v[40:43], v[132:135], v[112:115], v[36:39]
	s_waitcnt lgkmcnt(1)
	v_mfma_f32_16x16x32_bf16 v[36:39], v[136:139], v[112:115], v[32:35]
	s_waitcnt lgkmcnt(0)
	v_mfma_f32_16x16x32_bf16 v[32:35], v[140:143], v[112:115], v[28:31]
	v_mfma_f32_16x16x32_bf16 v[28:31], v[82:85], v[116:119], v[24:27]
	v_mfma_f32_16x16x32_bf16 v[24:27], v[108:111], v[116:119], v[20:23]
	v_mfma_f32_16x16x32_bf16 v[20:23], v[120:123], v[116:119], v[16:19]
	v_mfma_f32_16x16x32_bf16 v[16:19], v[124:127], v[116:119], v[12:15]
	v_mfma_f32_16x16x32_bf16 v[12:15], v[128:131], v[116:119], v[8:11]
	v_mfma_f32_16x16x32_bf16 v[8:11], v[132:135], v[116:119], v[4:7]
	v_mfma_f32_16x16x32_bf16 v[4:7], v[136:139], v[116:119], v[0:3]
	v_mfma_f32_16x16x32_bf16 v[0:3], v[140:143], v[116:119], v[104:107]
	s_cbranch_scc0 .LBB0_1224
	s_add_i32 s40, s54, s53
	v_add_u32_e32 v64, s40, v70
	v_cmp_lt_i32_e32 vcc, s48, v64
	s_and_saveexec_b64 s[2:3], vcc
	s_cbranch_execz .LBB0_1221
	v_lshl_add_u32 v64, v64, 5, v102
	v_lshlrev_b64 v[108:109], 2, v[64:65]
	v_lshl_add_u64 v[104:105], v[76:77], 0, v[108:109]
	global_load_dwordx4 v[82:85], v[104:105], off
	s_nop 0
	global_load_dwordx4 v[104:107], v[104:105], off offset:16
	v_lshl_add_u64 v[112:113], v[74:75], 0, v[108:109]
	global_load_dwordx4 v[108:111], v[112:113], off
	s_nop 0
	global_load_dwordx4 v[112:115], v[112:113], off offset:16
	s_waitcnt vmcnt(3)
	v_pk_mul_f32 v[116:117], v[54:55], v[84:85]
	v_pk_mul_f32 v[118:119], v[52:53], v[82:83]
	v_pk_mul_f32 v[120:121], v[62:63], v[84:85]
	v_pk_mul_f32 v[122:123], v[60:61], v[82:83]
	s_waitcnt vmcnt(2)
	v_pk_mul_f32 v[124:125], v[50:51], v[106:107]
	v_pk_mul_f32 v[126:127], v[48:49], v[104:105]
	v_pk_mul_f32 v[128:129], v[58:59], v[106:107]
	v_pk_mul_f32 v[130:131], v[56:57], v[104:105]
	v_pk_mul_f32 v[132:133], v[38:39], v[84:85]
	v_pk_mul_f32 v[134:135], v[36:37], v[82:83]
	v_pk_mul_f32 v[84:85], v[46:47], v[84:85]
	v_pk_mul_f32 v[82:83], v[44:45], v[82:83]
	v_pk_mul_f32 v[136:137], v[34:35], v[106:107]
	v_pk_mul_f32 v[138:139], v[32:33], v[104:105]
	v_pk_mul_f32 v[106:107], v[42:43], v[106:107]
	v_pk_mul_f32 v[104:105], v[40:41], v[104:105]
	s_waitcnt vmcnt(1)
	v_pk_fma_f32 v[62:63], v[62:63], v[110:111], v[116:117] neg_lo:[0,0,1] neg_hi:[0,0,1]
	v_pk_fma_f32 v[60:61], v[60:61], v[108:109], v[118:119] neg_lo:[0,0,1] neg_hi:[0,0,1]
	v_pk_fma_f32 v[54:55], v[54:55], v[110:111], v[120:121]
	v_pk_fma_f32 v[52:53], v[52:53], v[108:109], v[122:123]
	s_waitcnt vmcnt(0)
	v_pk_fma_f32 v[58:59], v[58:59], v[114:115], v[124:125] neg_lo:[0,0,1] neg_hi:[0,0,1]
	v_pk_fma_f32 v[56:57], v[56:57], v[112:113], v[126:127] neg_lo:[0,0,1] neg_hi:[0,0,1]
	v_pk_fma_f32 v[50:51], v[50:51], v[114:115], v[128:129]
	v_pk_fma_f32 v[48:49], v[48:49], v[112:113], v[130:131]
	v_pk_fma_f32 v[46:47], v[46:47], v[110:111], v[132:133] neg_lo:[0,0,1] neg_hi:[0,0,1]
	v_pk_fma_f32 v[44:45], v[44:45], v[108:109], v[134:135] neg_lo:[0,0,1] neg_hi:[0,0,1]
	v_pk_fma_f32 v[38:39], v[38:39], v[110:111], v[84:85]
	v_pk_fma_f32 v[36:37], v[36:37], v[108:109], v[82:83]
	v_pk_fma_f32 v[42:43], v[42:43], v[114:115], v[136:137] neg_lo:[0,0,1] neg_hi:[0,0,1]
	v_pk_fma_f32 v[40:41], v[40:41], v[112:113], v[138:139] neg_lo:[0,0,1] neg_hi:[0,0,1]
	v_pk_fma_f32 v[34:35], v[34:35], v[114:115], v[106:107]
	v_pk_fma_f32 v[32:33], v[32:33], v[112:113], v[104:105]

.LBB0_1615:
	s_add_i32 s41, s39, 0x8000
	s_and_b32 s40, s41, 0x8000
	s_add_i32 s40, s40, 0
	s_add_u32 s86, s40, s87
	s_mov_b32 m0, s86
	s_waitcnt vmcnt(0) lgkmcnt(0)
	s_barrier
	s_and_b32 s39, s39, 0x8000
	s_add_i32 s39, s39, 0
	v_add3_u32 v145, s39, v84, v85
	v_add3_u32 v178, s39, v85, v86
	v_add3_u32 v179, s39, v84, v87
	v_add3_u32 v180, s39, v86, v87
	global_load_lds_dwordx4 v244, s[96:97]
	s_add_u32 m0, s86, 0x4000
	ds_read_b128 v[104:107], v178
	global_load_lds_dwordx4 v245, s[88:89]
	s_add_u32 m0, s86, 0x1000
	ds_read_b128 v[76:79], v145 offset:16384
	global_load_lds_dwordx4 v246, s[96:97]
	s_add_u32 m0, s86, 0x5000
	ds_read_b128 v[100:103], v145 offset:18432
	global_load_lds_dwordx4 v247, s[88:89]
	s_add_u32 m0, s86, 0x2000
	ds_read_b128 v[108:111], v178 offset:2048
	global_load_lds_dwordx4 v248, s[96:97]
	s_add_u32 m0, s86, 0x6000
	ds_read_b128 v[112:115], v145 offset:20480
	global_load_lds_dwordx4 v249, s[88:89]
	s_add_u32 m0, s86, 0x3000
	ds_read_b128 v[116:119], v145 offset:22528
	global_load_lds_dwordx4 v250, s[96:97]
	s_add_u32 m0, s86, 0x7000
	ds_read_b128 v[120:123], v145 offset:24576
	global_load_lds_dwordx4 v251, s[88:89]
	s_add_u32 s96, s96, 0x80
	s_addc_u32 s97, s97, 0
	s_add_u32 s88, s88, 0x80
	s_addc_u32 s89, s89, 0
	ds_read_b128 v[124:127], v145 offset:26624
	ds_read_b128 v[128:131], v145 offset:28672
	ds_read_b128 v[132:135], v145 offset:30720
	ds_read_b128 v[146:149], v180
	ds_read_b128 v[136:139], v179 offset:16384
	ds_read_b128 v[140:143], v179 offset:18432
	ds_read_b128 v[150:153], v180 offset:2048
	ds_read_b128 v[154:157], v179 offset:20480
	ds_read_b128 v[158:161], v179 offset:22528
	ds_read_b128 v[162:165], v179 offset:24576
	ds_read_b128 v[166:169], v179 offset:26624
	ds_read_b128 v[170:173], v179 offset:28672
	ds_read_b128 v[174:177], v179 offset:30720
	s_add_u32 s28, s28, 0x80
	s_addc_u32 s29, s29, 0
	s_cmpk_eq_i32 s28, 0x780
	s_mov_b32 s39, s41
	s_waitcnt lgkmcnt(15)
	v_mfma_f32_16x16x32_bf16 v[60:63], v[76:79], v[104:107], v[60:63]
	v_mfma_f32_16x16x32_bf16 v[56:59], v[100:103], v[104:107], v[56:59]
	v_mfma_f32_16x16x32_bf16 v[24:27], v[76:79], v[108:111], v[24:27]
	v_mfma_f32_16x16x32_bf16 v[20:23], v[100:103], v[108:111], v[20:23]
	v_mfma_f32_16x16x32_bf16 v[52:55], v[112:115], v[104:107], v[52:55]
	v_mfma_f32_16x16x32_bf16 v[16:19], v[112:115], v[108:111], v[16:19]
	s_waitcnt lgkmcnt(14)
	v_mfma_f32_16x16x32_bf16 v[48:51], v[116:119], v[104:107], v[48:51]
	v_mfma_f32_16x16x32_bf16 v[12:15], v[116:119], v[108:111], v[12:15]
	s_waitcnt lgkmcnt(13)
	v_mfma_f32_16x16x32_bf16 v[44:47], v[120:123], v[104:107], v[44:47]
	v_mfma_f32_16x16x32_bf16 v[8:11], v[120:123], v[108:111], v[8:11]
	s_waitcnt lgkmcnt(12)
	v_mfma_f32_16x16x32_bf16 v[40:43], v[124:127], v[104:107], v[40:43]
	v_mfma_f32_16x16x32_bf16 v[4:7], v[124:127], v[108:111], v[4:7]
	s_waitcnt lgkmcnt(11)
	v_mfma_f32_16x16x32_bf16 v[32:35], v[128:131], v[104:107], v[32:35]
	v_mfma_f32_16x16x32_bf16 v[0:3], v[128:131], v[108:111], v[0:3]
	s_waitcnt lgkmcnt(10)
	v_mfma_f32_16x16x32_bf16 v[28:31], v[132:135], v[104:107], v[28:31]
	v_mfma_f32_16x16x32_bf16 v[36:39], v[132:135], v[108:111], v[36:39]
	s_waitcnt lgkmcnt(8)
	v_mfma_f32_16x16x32_bf16 v[60:63], v[136:139], v[146:149], v[60:63]
	s_waitcnt lgkmcnt(7)
	v_mfma_f32_16x16x32_bf16 v[56:59], v[140:143], v[146:149], v[56:59]
	s_waitcnt lgkmcnt(6)
	v_mfma_f32_16x16x32_bf16 v[24:27], v[136:139], v[150:153], v[24:27]
	v_mfma_f32_16x16x32_bf16 v[20:23], v[140:143], v[150:153], v[20:23]
	s_waitcnt lgkmcnt(5)
	v_mfma_f32_16x16x32_bf16 v[52:55], v[154:157], v[146:149], v[52:55]
	v_mfma_f32_16x16x32_bf16 v[16:19], v[154:157], v[150:153], v[16:19]
	s_waitcnt lgkmcnt(4)
	v_mfma_f32_16x16x32_bf16 v[48:51], v[158:161], v[146:149], v[48:51]
	v_mfma_f32_16x16x32_bf16 v[12:15], v[158:161], v[150:153], v[12:15]
	s_waitcnt lgkmcnt(3)
	v_mfma_f32_16x16x32_bf16 v[44:47], v[162:165], v[146:149], v[44:47]
	v_mfma_f32_16x16x32_bf16 v[8:11], v[162:165], v[150:153], v[8:11]
	s_waitcnt lgkmcnt(2)
	v_mfma_f32_16x16x32_bf16 v[40:43], v[166:169], v[146:149], v[40:43]
	v_mfma_f32_16x16x32_bf16 v[4:7], v[166:169], v[150:153], v[4:7]
	s_waitcnt lgkmcnt(1)
	v_mfma_f32_16x16x32_bf16 v[32:35], v[170:173], v[146:149], v[32:35]
	v_mfma_f32_16x16x32_bf16 v[0:3], v[170:173], v[150:153], v[0:3]
	s_waitcnt lgkmcnt(0)
	v_mfma_f32_16x16x32_bf16 v[28:31], v[174:177], v[146:149], v[28:31]
	v_mfma_f32_16x16x32_bf16 v[36:39], v[174:177], v[150:153], v[36:39]
	s_cbranch_scc0 .LBB0_1615
	v_add_u32_e32 v80, s40, v84
	v_add_u32_e32 v81, v80, v85
	s_waitcnt vmcnt(0)
	s_barrier
	ds_read_b128 v[72:75], v81 offset:16384
	v_add3_u32 v99, s40, v85, v86
	ds_read_b128 v[76:79], v81 offset:18432
	ds_read_b128 v[100:103], v99
	ds_read_b128 v[104:107], v99 offset:2048
	ds_read_b128 v[108:111], v81 offset:20480
	ds_read_b128 v[112:115], v81 offset:22528
	ds_read_b128 v[116:119], v81 offset:24576
	ds_read_b128 v[120:123], v81 offset:26624
	ds_read_b128 v[124:127], v81 offset:28672
	ds_read_b128 v[128:131], v81 offset:30720
	v_add_u32_e32 v80, v80, v87
	s_waitcnt lgkmcnt(7)
	v_mfma_f32_16x16x32_bf16 v[60:63], v[72:75], v[100:103], v[60:63]
	s_lshl_b32 s38, s38, 7
	v_mfma_f32_16x16x32_bf16 v[56:59], v[76:79], v[100:103], v[56:59]
	s_waitcnt lgkmcnt(4)
	v_mfma_f32_16x16x32_bf16 v[48:51], v[112:115], v[100:103], v[48:51]
	s_waitcnt lgkmcnt(3)
	v_mfma_f32_16x16x32_bf16 v[44:47], v[116:119], v[100:103], v[44:47]
	s_waitcnt lgkmcnt(2)
	v_mfma_f32_16x16x32_bf16 v[40:43], v[120:123], v[100:103], v[40:43]
	s_waitcnt lgkmcnt(1)
	v_mfma_f32_16x16x32_bf16 v[32:35], v[124:127], v[100:103], v[32:35]
	s_waitcnt lgkmcnt(0)
	v_mfma_f32_16x16x32_bf16 v[28:31], v[128:131], v[100:103], v[28:31]
	v_mfma_f32_16x16x32_bf16 v[24:27], v[72:75], v[104:107], v[24:27]
	ds_read_b128 v[72:75], v80 offset:16384
	v_mfma_f32_16x16x32_bf16 v[52:55], v[108:111], v[100:103], v[52:55]
	v_mfma_f32_16x16x32_bf16 v[20:23], v[76:79], v[104:107], v[20:23]
	v_mfma_f32_16x16x32_bf16 v[16:19], v[108:111], v[104:107], v[16:19]
	v_mfma_f32_16x16x32_bf16 v[12:15], v[112:115], v[104:107], v[12:15]
	v_mfma_f32_16x16x32_bf16 v[8:11], v[116:119], v[104:107], v[8:11]
	v_mfma_f32_16x16x32_bf16 v[4:7], v[120:123], v[104:107], v[4:7]
	v_mfma_f32_16x16x32_bf16 v[0:3], v[124:127], v[104:107], v[0:3]
	v_mfma_f32_16x16x32_bf16 v[100:103], v[128:131], v[104:107], v[36:39]
	s_nop 2
	v_add3_u32 v36, s40, v87, v86
	ds_read_b128 v[76:79], v80 offset:18432
	ds_read_b128 v[104:107], v36
	ds_read_b128 v[108:111], v36 offset:2048
	ds_read_b128 v[128:131], v80 offset:28672
	ds_read_b128 v[132:135], v80 offset:30720
	ds_read_b128 v[112:115], v80 offset:20480
	ds_read_b128 v[116:119], v80 offset:22528
	ds_read_b128 v[120:123], v80 offset:24576
	ds_read_b128 v[124:127], v80 offset:26624
	s_waitcnt lgkmcnt(7)
	v_mfma_f32_16x16x32_bf16 v[60:63], v[72:75], v[104:107], v[60:63]
	s_waitcnt lgkmcnt(5)
	v_mfma_f32_16x16x32_bf16 v[36:39], v[128:131], v[104:107], v[32:35]
	s_waitcnt lgkmcnt(4)
	v_mfma_f32_16x16x32_bf16 v[32:35], v[132:135], v[104:107], v[28:31]
	v_mfma_f32_16x16x32_bf16 v[28:31], v[72:75], v[108:111], v[24:27]
	v_add_u32_e32 v72, s38, v83
	v_mul_hi_i32 v73, v72, s31
	v_mfma_f32_16x16x32_bf16 v[24:27], v[76:79], v[108:111], v[20:23]
	s_waitcnt lgkmcnt(3)
	v_mfma_f32_16x16x32_bf16 v[20:23], v[112:115], v[108:111], v[16:19]
	s_waitcnt lgkmcnt(2)
	v_mfma_f32_16x16x32_bf16 v[16:19], v[116:119], v[108:111], v[12:15]
	s_waitcnt lgkmcnt(1)
	v_mfma_f32_16x16x32_bf16 v[12:15], v[120:123], v[108:111], v[8:11]
	s_waitcnt lgkmcnt(0)
	v_mfma_f32_16x16x32_bf16 v[8:11], v[124:127], v[108:111], v[4:7]
	s_nop 2
	v_lshrrev_b32_e32 v4, 31, v73
	v_ashrrev_i32_e32 v5, 11, v73
	v_mfma_f32_16x16x32_bf16 v[56:59], v[76:79], v[104:107], v[56:59]
	v_add_u32_e32 v73, v5, v4
	v_mad_i32_i24 v78, v73, s33, v72
	v_lshlrev_b32_e32 v75, 13, v73
	v_mfma_f32_16x16x32_bf16 v[52:55], v[112:115], v[104:107], v[52:55]
	v_cmp_lt_i32_e32 vcc, s34, v78
	v_add3_u32 v74, v75, v78, s35
	v_mfma_f32_16x16x32_bf16 v[48:51], v[116:119], v[104:107], v[48:51]
	v_mfma_f32_16x16x32_bf16 v[44:47], v[120:123], v[104:107], v[44:47]
	v_mfma_f32_16x16x32_bf16 v[40:43], v[124:127], v[104:107], v[40:43]
	v_mfma_f32_16x16x32_bf16 v[4:7], v[128:131], v[108:111], v[0:3]
	v_mfma_f32_16x16x32_bf16 v[0:3], v[132:135], v[108:111], v[100:103]
	s_and_saveexec_b64 s[28:29], vcc
	s_xor_b64 s[28:29], exec, s[28:29]
	v_add3_u32 v72, v75, v78, s35
	s_or_saveexec_b64 s[28:29], s[28:29]
	v_mov_b64_e32 v[76:77], s[92:93]
	v_lshl_add_u32 v75, v73, 8, v78
	s_xor_b64 exec, exec, s[28:29]
	v_lshl_add_u32 v72, v73, 8, v78
	v_mov_b64_e32 v[76:77], s[2:3]
	s_or_b64 exec, exec, s[28:29]
	s_and_saveexec_b64 s[28:29], vcc
	s_xor_b64 s[28:29], exec, s[28:29]
	s_cbranch_execz .LBB0_1622
	v_add_u32_e32 v73, 3, v73
	v_mul_hi_i32_i24_e32 v79, 0x6000, v73
	v_mul_i32_i24_e32 v78, 0x6000, v73
	s_or_saveexec_b64 s[28:29], s[28:29]
	v_mov_b64_e32 v[80:81], s[92:93]
	s_xor_b64 exec, exec, s[28:29]
	s_cbranch_execnz .LBB0_1623
	s_branch .LBB0_1624

.LBB0_1759:
	s_add_i32 s36, s34, 0x8000
	s_and_b32 s35, s36, 0x8000
	s_add_i32 s35, s35, 0
	s_add_u32 s86, s35, s87
	s_mov_b32 m0, s86
	s_waitcnt vmcnt(0) lgkmcnt(0)
	s_barrier
	s_and_b32 s34, s34, 0x8000
	s_add_i32 s34, s34, 0
	v_add3_u32 v143, s34, v80, v81
	v_add3_u32 v145, s34, v81, v82
	v_add3_u32 v206, s34, v80, v83
	v_add3_u32 v207, s34, v82, v83
	global_load_lds_dwordx4 v244, s[96:97]
	s_add_u32 m0, s86, 0x4000
	ds_read_b128 v[102:105], v145
	global_load_lds_dwordx4 v245, s[88:89]
	s_add_u32 m0, s86, 0x1000
	ds_read_b128 v[94:97], v143 offset:16384
	global_load_lds_dwordx4 v246, s[96:97]
	s_add_u32 m0, s86, 0x5000
	ds_read_b128 v[98:101], v143 offset:18432
	global_load_lds_dwordx4 v247, s[88:89]
	s_add_u32 m0, s86, 0x2000
	ds_read_b128 v[106:109], v145 offset:2048
	global_load_lds_dwordx4 v248, s[96:97]
	s_add_u32 m0, s86, 0x6000
	ds_read_b128 v[110:113], v143 offset:20480
	global_load_lds_dwordx4 v249, s[88:89]
	s_add_u32 m0, s86, 0x3000
	ds_read_b128 v[114:117], v143 offset:22528
	global_load_lds_dwordx4 v250, s[96:97]
	s_add_u32 m0, s86, 0x7000
	ds_read_b128 v[118:121], v143 offset:24576
	global_load_lds_dwordx4 v251, s[88:89]
	s_add_u32 s96, s96, 0x80
	s_addc_u32 s97, s97, 0
	s_add_u32 s88, s88, 0x80
	s_addc_u32 s89, s89, 0
	ds_read_b128 v[122:125], v143 offset:26624
	ds_read_b128 v[126:129], v143 offset:28672
	ds_read_b128 v[130:133], v143 offset:30720
	ds_read_b128 v[174:177], v207
	ds_read_b128 v[166:169], v206 offset:16384
	ds_read_b128 v[170:173], v206 offset:18432
	ds_read_b128 v[178:181], v207 offset:2048
	ds_read_b128 v[182:185], v206 offset:20480
	ds_read_b128 v[186:189], v206 offset:22528
	ds_read_b128 v[190:193], v206 offset:24576
	ds_read_b128 v[194:197], v206 offset:26624
	ds_read_b128 v[198:201], v206 offset:28672
	ds_read_b128 v[202:205], v206 offset:30720
	s_add_u32 s26, s26, 0x80
	s_addc_u32 s27, s27, 0
	s_cmpk_eq_i32 s26, 0x780
	s_mov_b32 s34, s36
	s_waitcnt lgkmcnt(15)
	v_mfma_f32_16x16x32_bf16 v[60:63], v[94:97], v[102:105], v[60:63]
	v_mfma_f32_16x16x32_bf16 v[56:59], v[98:101], v[102:105], v[56:59]
	v_mfma_f32_16x16x32_bf16 v[28:31], v[94:97], v[106:109], v[28:31]
	v_mfma_f32_16x16x32_bf16 v[24:27], v[98:101], v[106:109], v[24:27]
	v_mfma_f32_16x16x32_bf16 v[52:55], v[110:113], v[102:105], v[52:55]
	v_mfma_f32_16x16x32_bf16 v[20:23], v[110:113], v[106:109], v[20:23]
	s_waitcnt lgkmcnt(14)
	v_mfma_f32_16x16x32_bf16 v[48:51], v[114:117], v[102:105], v[48:51]
	v_mfma_f32_16x16x32_bf16 v[12:15], v[114:117], v[106:109], v[12:15]
	s_waitcnt lgkmcnt(13)
	v_mfma_f32_16x16x32_bf16 v[44:47], v[118:121], v[102:105], v[44:47]
	v_mfma_f32_16x16x32_bf16 v[8:11], v[118:121], v[106:109], v[8:11]
	s_waitcnt lgkmcnt(12)
	v_mfma_f32_16x16x32_bf16 v[40:43], v[122:125], v[102:105], v[40:43]
	v_mfma_f32_16x16x32_bf16 v[4:7], v[122:125], v[106:109], v[4:7]
	s_waitcnt lgkmcnt(11)
	v_mfma_f32_16x16x32_bf16 v[36:39], v[126:129], v[102:105], v[36:39]
	v_mfma_f32_16x16x32_bf16 v[0:3], v[126:129], v[106:109], v[0:3]
	s_waitcnt lgkmcnt(10)
	v_mfma_f32_16x16x32_bf16 v[32:35], v[130:133], v[102:105], v[32:35]
	v_mfma_f32_16x16x32_bf16 v[16:19], v[130:133], v[106:109], v[16:19]
	s_waitcnt lgkmcnt(8)
	v_mfma_f32_16x16x32_bf16 v[60:63], v[166:169], v[174:177], v[60:63]
	s_waitcnt lgkmcnt(7)
	v_mfma_f32_16x16x32_bf16 v[56:59], v[170:173], v[174:177], v[56:59]
	s_waitcnt lgkmcnt(6)
	v_mfma_f32_16x16x32_bf16 v[28:31], v[166:169], v[178:181], v[28:31]
	v_mfma_f32_16x16x32_bf16 v[24:27], v[170:173], v[178:181], v[24:27]
	s_waitcnt lgkmcnt(5)
	v_mfma_f32_16x16x32_bf16 v[52:55], v[182:185], v[174:177], v[52:55]
	v_mfma_f32_16x16x32_bf16 v[20:23], v[182:185], v[178:181], v[20:23]
	s_waitcnt lgkmcnt(4)
	v_mfma_f32_16x16x32_bf16 v[48:51], v[186:189], v[174:177], v[48:51]
	v_mfma_f32_16x16x32_bf16 v[12:15], v[186:189], v[178:181], v[12:15]
	s_waitcnt lgkmcnt(3)
	v_mfma_f32_16x16x32_bf16 v[44:47], v[190:193], v[174:177], v[44:47]
	v_mfma_f32_16x16x32_bf16 v[8:11], v[190:193], v[178:181], v[8:11]
	s_waitcnt lgkmcnt(2)
	v_mfma_f32_16x16x32_bf16 v[40:43], v[194:197], v[174:177], v[40:43]
	v_mfma_f32_16x16x32_bf16 v[4:7], v[194:197], v[178:181], v[4:7]
	s_waitcnt lgkmcnt(1)
	v_mfma_f32_16x16x32_bf16 v[36:39], v[198:201], v[174:177], v[36:39]
	v_mfma_f32_16x16x32_bf16 v[0:3], v[198:201], v[178:181], v[0:3]
	s_waitcnt lgkmcnt(0)
	v_mfma_f32_16x16x32_bf16 v[32:35], v[202:205], v[174:177], v[32:35]
	v_mfma_f32_16x16x32_bf16 v[16:19], v[202:205], v[178:181], v[16:19]
	s_cbranch_scc0 .LBB0_1759
	v_add_u32_e32 v138, s35, v80
	v_add_u32_e32 v126, v138, v81
	s_waitcnt vmcnt(0)
	s_barrier
	ds_read_b128 v[74:77], v126 offset:16384
	v_add3_u32 v102, s35, v81, v82
	ds_read_b128 v[94:97], v102
	ds_read_b128 v[98:101], v126 offset:18432
	ds_read_b128 v[102:105], v102 offset:2048
	ds_read_b128 v[106:109], v126 offset:20480
	ds_read_b128 v[110:113], v126 offset:22528
	ds_read_b128 v[114:117], v126 offset:24576
	ds_read_b128 v[118:121], v126 offset:26624
	v_add3_u32 v134, s35, v83, v82
	v_add_u32_e32 v142, v138, v83
	ds_read_b128 v[122:125], v126 offset:28672
	ds_read_b128 v[126:129], v126 offset:30720
	ds_read_b128 v[130:133], v134
	ds_read_b128 v[134:137], v134 offset:2048
	ds_read_b128 v[138:141], v142 offset:16384
	ds_read_b128 v[146:149], v142 offset:18432
	s_waitcnt lgkmcnt(11)
	v_mfma_f32_16x16x32_bf16 v[56:59], v[98:101], v[94:97], v[56:59]
	s_lshl_b32 s33, s33, 7
	s_lshl_b32 s26, s31, 7
	s_ashr_i32 s27, s26, 31
	v_mfma_f32_16x16x32_bf16 v[60:63], v[74:77], v[94:97], v[60:63]
	s_lshl_b64 s[26:27], s[26:27], 1
	s_add_i32 s30, s30, s28
	s_cmpk_gt_i32 s30, 0xfff
	s_waitcnt lgkmcnt(0)
	v_mfma_f32_16x16x32_bf16 v[56:59], v[146:149], v[130:133], v[56:59]
	v_mfma_f32_16x16x32_bf16 v[48:51], v[110:113], v[94:97], v[48:51]
	v_mfma_f32_16x16x32_bf16 v[52:55], v[106:109], v[94:97], v[52:55]
	s_nop 5
	v_max_f32_e32 v56, v56, v56
	v_max_f32_e32 v57, v57, v57
	v_max_f32_e32 v56, 0, v56
	v_mfma_f32_16x16x32_bf16 v[44:47], v[114:117], v[94:97], v[44:47]
	v_max_f32_e32 v57, 0, v57
	v_max_f32_e32 v59, v59, v59
	v_max_f32_e32 v59, 0, v59
	v_mfma_f32_16x16x32_bf16 v[40:43], v[118:121], v[94:97], v[40:43]
	v_mfma_f32_16x16x32_bf16 v[36:39], v[122:125], v[94:97], v[36:39]
	v_mfma_f32_16x16x32_bf16 v[32:35], v[126:129], v[94:97], v[32:35]
	ds_read_b128 v[94:97], v142 offset:20480
	ds_read_b128 v[150:153], v142 offset:22528
	ds_read_b128 v[154:157], v142 offset:24576
	ds_read_b128 v[158:161], v142 offset:26624
	v_mfma_f32_16x16x32_bf16 v[60:63], v[138:141], v[130:133], v[60:63]
	s_waitcnt lgkmcnt(2)
	v_mfma_f32_16x16x32_bf16 v[48:51], v[150:153], v[130:133], v[48:51]
	v_mfma_f32_16x16x32_bf16 v[20:23], v[106:109], v[102:105], v[20:23]
	v_mul_f32_e64 v106, v56, v56
	v_mul_f32_e64 v107, v57, v57
	v_max_f32_e32 v57, v58, v58
	s_nop 1
	v_max_f32_e32 v60, v60, v60
	v_mfma_f32_16x16x32_bf16 v[24:27], v[98:101], v[102:105], v[24:27]
	v_add_u32_e32 v100, s33, v79
	v_mov_b64_e32 v[98:99], s[0:1]
	v_max_f32_e32 v61, v61, v61
	v_max_f32_e32 v56, v62, v62
	v_max_f32_e32 v58, 0, v57
	v_max_f32_e32 v57, v63, v63
	v_mad_i64_i32 v[100:101], s[34:35], v100, s29, v[98:99]
	v_max_f32_e32 v60, 0, v60
	v_max_f32_e32 v61, 0, v61
	v_max_f32_e32 v56, 0, v56
	v_max_f32_e32 v57, 0, v57
	v_mfma_f32_16x16x32_bf16 v[52:55], v[94:97], v[130:133], v[52:55]
	v_lshl_add_u64 v[100:101], v[100:101], 0, s[26:27]
	v_pk_mul_f32 v[60:61], v[60:61], v[60:61]
	v_pk_mul_f32 v[62:63], v[56:57], v[56:57]
	v_mfma_f32_16x16x32_bf16 v[28:31], v[74:77], v[102:105], v[28:31]
	v_max_f32_e32 v48, v48, v48
	v_max_f32_e32 v49, v49, v49
	ds_read_b128 v[74:77], v142 offset:28672
	ds_read_b128 v[162:165], v142 offset:30720
	v_mfma_f32_16x16x32_bf16 v[12:15], v[110:113], v[102:105], v[12:15]
	v_lshl_add_u64 v[100:101], v[100:101], 0, v[64:65]
	v_cvt_pk_bf16_f32 v56, v60, v61
	v_cvt_pk_bf16_f32 v57, v62, v63
	v_mfma_f32_16x16x32_bf16 v[8:11], v[114:117], v[102:105], v[8:11]
	v_max_f32_e32 v48, 0, v48
	v_max_f32_e32 v49, 0, v49
	v_max_f32_e32 v52, v52, v52
	v_mfma_f32_16x16x32_bf16 v[4:7], v[118:121], v[102:105], v[4:7]
	v_max_f32_e32 v53, v53, v53
	v_max_f32_e32 v51, v51, v51
	v_max_f32_e32 v52, 0, v52
	v_mfma_f32_16x16x32_bf16 v[0:3], v[122:125], v[102:105], v[0:3]
	v_max_f32_e32 v53, 0, v53
	v_max_f32_e32 v51, 0, v51
	v_pk_mul_f32 v[52:53], v[52:53], v[52:53]
	v_mfma_f32_16x16x32_bf16 v[16:19], v[126:129], v[102:105], v[16:19]
	v_mul_f32_e64 v102, v58, v58
	v_mul_f32_e64 v103, v59, v59
	v_cvt_pk_bf16_f32 v58, v106, v107
	v_cvt_pk_bf16_f32 v59, v102, v103
	s_waitcnt lgkmcnt(2)
	v_mfma_f32_16x16x32_bf16 v[40:43], v[158:161], v[130:133], v[40:43]
	global_store_dwordx4 v[100:101], v[56:59], off
	s_nop 1
	v_pk_mul_f32 v[56:57], v[48:49], v[48:49]
	v_max_f32_e32 v49, v50, v50
	v_max_f32_e32 v48, v54, v54
	v_max_f32_e32 v50, 0, v49
	v_max_f32_e32 v49, v55, v55
	v_mfma_f32_16x16x32_bf16 v[44:47], v[154:157], v[130:133], v[44:47]
	v_max_f32_e32 v48, 0, v48
	v_max_f32_e32 v49, 0, v49
	v_pk_mul_f32 v[54:55], v[48:49], v[48:49]
	v_pk_mul_f32 v[58:59], v[50:51], v[50:51]
	v_max_f32_e32 v40, v40, v40
	v_max_f32_e32 v41, v41, v41
	s_waitcnt lgkmcnt(0)
	v_mfma_f32_16x16x32_bf16 v[32:35], v[162:165], v[130:133], v[32:35]
	v_cvt_pk_bf16_f32 v48, v52, v53
	v_cvt_pk_bf16_f32 v49, v54, v55
	v_cvt_pk_bf16_f32 v50, v56, v57
	v_cvt_pk_bf16_f32 v51, v58, v59
	v_max_f32_e32 v40, 0, v40
	v_max_f32_e32 v41, 0, v41
	global_store_dwordx4 v[100:101], v[48:51], off offset:64
	v_max_f32_e32 v44, v44, v44
	v_max_f32_e32 v45, v45, v45
	v_pk_mul_f32 v[48:49], v[40:41], v[40:41]
	v_max_f32_e32 v41, v42, v42
	v_max_f32_e32 v40, v46, v46
	v_max_f32_e32 v42, 0, v41
	v_max_f32_e32 v41, v47, v47
	v_max_f32_e32 v43, v43, v43
	v_mfma_f32_16x16x32_bf16 v[36:39], v[74:77], v[130:133], v[36:39]
	v_max_f32_e32 v44, 0, v44
	v_max_f32_e32 v45, 0, v45
	v_max_f32_e32 v40, 0, v40
	v_max_f32_e32 v41, 0, v41
	v_max_f32_e32 v43, 0, v43
	v_pk_mul_f32 v[44:45], v[44:45], v[44:45]
	v_pk_mul_f32 v[46:47], v[40:41], v[40:41]
	v_pk_mul_f32 v[50:51], v[42:43], v[42:43]
	v_max_f32_e32 v32, v32, v32
	v_max_f32_e32 v33, v33, v33
	v_mfma_f32_16x16x32_bf16 v[24:27], v[146:149], v[134:137], v[24:27]
	v_cvt_pk_bf16_f32 v40, v44, v45
	v_cvt_pk_bf16_f32 v41, v46, v47
	v_cvt_pk_bf16_f32 v42, v48, v49
	v_cvt_pk_bf16_f32 v43, v50, v51
	v_max_f32_e32 v32, 0, v32
	v_max_f32_e32 v33, 0, v33
	global_store_dwordx4 v[100:101], v[40:43], off offset:128
	v_max_f32_e32 v36, v36, v36
	v_max_f32_e32 v37, v37, v37
	v_pk_mul_f32 v[40:41], v[32:33], v[32:33]
	v_max_f32_e32 v33, v34, v34
	v_max_f32_e32 v32, v38, v38
	v_max_f32_e32 v34, 0, v33
	v_max_f32_e32 v33, v39, v39
	v_max_f32_e32 v35, v35, v35
	v_mfma_f32_16x16x32_bf16 v[28:31], v[138:141], v[134:137], v[28:31]
	v_max_f32_e32 v36, 0, v36
	v_max_f32_e32 v37, 0, v37
	v_max_f32_e32 v32, 0, v32
	v_max_f32_e32 v33, 0, v33
	v_max_f32_e32 v35, 0, v35
	v_pk_mul_f32 v[36:37], v[36:37], v[36:37]
	v_pk_mul_f32 v[38:39], v[32:33], v[32:33]
	v_pk_mul_f32 v[42:43], v[34:35], v[34:35]
	v_max_f32_e32 v24, v24, v24
	v_max_f32_e32 v25, v25, v25
	v_mfma_f32_16x16x32_bf16 v[12:15], v[150:153], v[134:137], v[12:15]
	v_cvt_pk_bf16_f32 v32, v36, v37
	v_cvt_pk_bf16_f32 v33, v38, v39
	v_cvt_pk_bf16_f32 v34, v40, v41
	v_cvt_pk_bf16_f32 v35, v42, v43
	v_max_f32_e32 v24, 0, v24
	v_max_f32_e32 v25, 0, v25
	global_store_dwordx4 v[100:101], v[32:35], off offset:192
	v_max_f32_e32 v28, v28, v28
	v_max_f32_e32 v29, v29, v29
	v_pk_mul_f32 v[34:35], v[24:25], v[24:25]
	v_max_f32_e32 v25, v26, v26
	v_add_u32_e32 v32, s33, v84
	v_max_f32_e32 v24, v30, v30
	v_max_f32_e32 v26, 0, v25
	v_max_f32_e32 v25, v31, v31
	v_max_f32_e32 v27, v27, v27
	v_mfma_f32_16x16x32_bf16 v[20:23], v[94:97], v[134:137], v[20:23]
	v_mad_i64_i32 v[32:33], s[34:35], v32, s29, v[98:99]
	v_max_f32_e32 v28, 0, v28
	v_max_f32_e32 v29, 0, v29
	v_max_f32_e32 v24, 0, v24
	v_max_f32_e32 v25, 0, v25
	v_max_f32_e32 v27, 0, v27
	v_lshl_add_u64 v[32:33], v[32:33], 0, s[26:27]
	v_pk_mul_f32 v[28:29], v[28:29], v[28:29]
	v_pk_mul_f32 v[30:31], v[24:25], v[24:25]
	v_pk_mul_f32 v[36:37], v[26:27], v[26:27]
	v_max_f32_e32 v12, v12, v12
	v_max_f32_e32 v13, v13, v13
	v_mfma_f32_16x16x32_bf16 v[4:7], v[158:161], v[134:137], v[4:7]
	v_lshl_add_u64 v[32:33], v[32:33], 0, v[64:65]
	v_cvt_pk_bf16_f32 v24, v28, v29
	v_cvt_pk_bf16_f32 v25, v30, v31
	v_cvt_pk_bf16_f32 v26, v34, v35
	v_cvt_pk_bf16_f32 v27, v36, v37
	v_max_f32_e32 v12, 0, v12
	v_max_f32_e32 v13, 0, v13
	global_store_dwordx4 v[32:33], v[24:27], off
	v_max_f32_e32 v20, v20, v20
	v_max_f32_e32 v21, v21, v21
	v_pk_mul_f32 v[24:25], v[12:13], v[12:13]
	v_max_f32_e32 v13, v14, v14
	v_max_f32_e32 v12, v22, v22
	v_max_f32_e32 v14, 0, v13
	v_max_f32_e32 v13, v23, v23
	v_max_f32_e32 v15, v15, v15
	v_mfma_f32_16x16x32_bf16 v[8:11], v[154:157], v[134:137], v[8:11]
	v_max_f32_e32 v20, 0, v20
	v_max_f32_e32 v21, 0, v21
	v_max_f32_e32 v12, 0, v12
	v_max_f32_e32 v13, 0, v13
	v_max_f32_e32 v15, 0, v15
	v_pk_mul_f32 v[20:21], v[20:21], v[20:21]
	v_pk_mul_f32 v[22:23], v[12:13], v[12:13]
	v_pk_mul_f32 v[26:27], v[14:15], v[14:15]
	v_max_f32_e32 v4, v4, v4
	v_max_f32_e32 v5, v5, v5
	v_cvt_pk_bf16_f32 v12, v20, v21
	v_cvt_pk_bf16_f32 v13, v22, v23
	v_cvt_pk_bf16_f32 v14, v24, v25
	v_cvt_pk_bf16_f32 v15, v26, v27
	v_max_f32_e32 v4, 0, v4
	v_max_f32_e32 v5, 0, v5
	global_store_dwordx4 v[32:33], v[12:15], off offset:64
	v_mfma_f32_16x16x32_bf16 v[0:3], v[74:77], v[134:137], v[0:3]
	v_max_f32_e32 v8, v8, v8
	v_pk_mul_f32 v[12:13], v[4:5], v[4:5]
	v_max_f32_e32 v5, v6, v6
	v_mfma_f32_16x16x32_bf16 v[16:19], v[162:165], v[134:137], v[16:19]
	v_max_f32_e32 v9, v9, v9
	v_max_f32_e32 v4, v10, v10
	v_max_f32_e32 v6, 0, v5
	v_max_f32_e32 v5, v11, v11
	v_max_f32_e32 v7, v7, v7
	v_max_f32_e32 v8, 0, v8
	v_max_f32_e32 v9, 0, v9
	v_max_f32_e32 v4, 0, v4
	v_max_f32_e32 v5, 0, v5
	v_max_f32_e32 v7, 0, v7
	v_pk_mul_f32 v[8:9], v[8:9], v[8:9]
	v_pk_mul_f32 v[10:11], v[4:5], v[4:5]
	v_pk_mul_f32 v[14:15], v[6:7], v[6:7]
	v_cvt_pk_bf16_f32 v4, v8, v9
	v_cvt_pk_bf16_f32 v5, v10, v11
	v_cvt_pk_bf16_f32 v6, v12, v13
	v_cvt_pk_bf16_f32 v7, v14, v15
	global_store_dwordx4 v[32:33], v[4:7], off offset:128
	v_max_f32_e32 v0, v0, v0
	v_max_f32_e32 v1, v1, v1
	v_max_f32_e32 v4, v16, v16
	v_max_f32_e32 v5, v17, v17
	v_max_f32_e32 v2, v2, v2
	v_max_f32_e32 v6, v18, v18
	v_max_f32_e32 v3, v3, v3
	v_max_f32_e32 v7, v19, v19
	v_max_f32_e32 v0, 0, v0
	v_max_f32_e32 v4, 0, v4
	v_max_f32_e32 v1, 0, v1
	v_max_f32_e32 v5, 0, v5
	v_max_f32_e32 v2, 0, v2
	v_max_f32_e32 v6, 0, v6
	v_max_f32_e32 v3, 0, v3
	v_max_f32_e32 v7, 0, v7
	v_pk_mul_f32 v[0:1], v[0:1], v[0:1]
	v_pk_mul_f32 v[4:5], v[4:5], v[4:5]
	v_pk_mul_f32 v[2:3], v[2:3], v[2:3]
	v_pk_mul_f32 v[6:7], v[6:7], v[6:7]
	v_cvt_pk_bf16_f32 v0, v0, v1
	v_cvt_pk_bf16_f32 v1, v2, v3
	v_cvt_pk_bf16_f32 v2, v4, v5
	v_cvt_pk_bf16_f32 v3, v6, v7
	global_store_dwordx4 v[32:33], v[0:3], off offset:192
	s_cbranch_scc0 .LBB0_1754

.LBB0_1824:
	s_add_i32 s41, s39, 0x8000
	s_and_b32 s40, s41, 0x8000
	s_add_i32 s40, s40, 0
	s_add_u32 s86, s40, s87
	s_mov_b32 m0, s86
	s_waitcnt vmcnt(0) lgkmcnt(0)
	s_barrier
	s_and_b32 s39, s39, 0x8000
	s_add_i32 s39, s39, 0
	v_add3_u32 v145, s39, v84, v85
	v_add3_u32 v178, s39, v85, v86
	v_add3_u32 v179, s39, v84, v87
	v_add3_u32 v180, s39, v86, v87
	global_load_lds_dwordx4 v244, s[96:97]
	s_add_u32 m0, s86, 0x4000
	ds_read_b128 v[104:107], v178
	global_load_lds_dwordx4 v245, s[88:89]
	s_add_u32 m0, s86, 0x1000
	ds_read_b128 v[76:79], v145 offset:16384
	global_load_lds_dwordx4 v246, s[96:97]
	s_add_u32 m0, s86, 0x5000
	ds_read_b128 v[100:103], v145 offset:18432
	global_load_lds_dwordx4 v247, s[88:89]
	s_add_u32 m0, s86, 0x2000
	ds_read_b128 v[108:111], v178 offset:2048
	global_load_lds_dwordx4 v248, s[96:97]
	s_add_u32 m0, s86, 0x6000
	ds_read_b128 v[112:115], v145 offset:20480
	global_load_lds_dwordx4 v249, s[88:89]
	s_add_u32 m0, s86, 0x3000
	ds_read_b128 v[116:119], v145 offset:22528
	global_load_lds_dwordx4 v250, s[96:97]
	s_add_u32 m0, s86, 0x7000
	ds_read_b128 v[120:123], v145 offset:24576
	global_load_lds_dwordx4 v251, s[88:89]
	s_add_u32 s96, s96, 0x80
	s_addc_u32 s97, s97, 0
	s_add_u32 s88, s88, 0x80
	s_addc_u32 s89, s89, 0
	ds_read_b128 v[124:127], v145 offset:26624
	ds_read_b128 v[128:131], v145 offset:28672
	ds_read_b128 v[132:135], v145 offset:30720
	ds_read_b128 v[146:149], v180
	ds_read_b128 v[136:139], v179 offset:16384
	ds_read_b128 v[140:143], v179 offset:18432
	ds_read_b128 v[150:153], v180 offset:2048
	ds_read_b128 v[154:157], v179 offset:20480
	ds_read_b128 v[158:161], v179 offset:22528
	ds_read_b128 v[162:165], v179 offset:24576
	ds_read_b128 v[166:169], v179 offset:26624
	ds_read_b128 v[170:173], v179 offset:28672
	ds_read_b128 v[174:177], v179 offset:30720
	s_add_u32 s28, s28, 0x80
	s_addc_u32 s29, s29, 0
	s_cmpk_eq_i32 s28, 0x1f80
	s_mov_b32 s39, s41
	s_waitcnt lgkmcnt(15)
	v_mfma_f32_16x16x32_bf16 v[60:63], v[76:79], v[104:107], v[60:63]
	v_mfma_f32_16x16x32_bf16 v[56:59], v[100:103], v[104:107], v[56:59]
	v_mfma_f32_16x16x32_bf16 v[24:27], v[76:79], v[108:111], v[24:27]
	v_mfma_f32_16x16x32_bf16 v[20:23], v[100:103], v[108:111], v[20:23]
	v_mfma_f32_16x16x32_bf16 v[52:55], v[112:115], v[104:107], v[52:55]
	v_mfma_f32_16x16x32_bf16 v[16:19], v[112:115], v[108:111], v[16:19]
	s_waitcnt lgkmcnt(14)
	v_mfma_f32_16x16x32_bf16 v[48:51], v[116:119], v[104:107], v[48:51]
	v_mfma_f32_16x16x32_bf16 v[12:15], v[116:119], v[108:111], v[12:15]
	s_waitcnt lgkmcnt(13)
	v_mfma_f32_16x16x32_bf16 v[44:47], v[120:123], v[104:107], v[44:47]
	v_mfma_f32_16x16x32_bf16 v[8:11], v[120:123], v[108:111], v[8:11]
	s_waitcnt lgkmcnt(12)
	v_mfma_f32_16x16x32_bf16 v[40:43], v[124:127], v[104:107], v[40:43]
	v_mfma_f32_16x16x32_bf16 v[4:7], v[124:127], v[108:111], v[4:7]
	s_waitcnt lgkmcnt(11)
	v_mfma_f32_16x16x32_bf16 v[32:35], v[128:131], v[104:107], v[32:35]
	v_mfma_f32_16x16x32_bf16 v[0:3], v[128:131], v[108:111], v[0:3]
	s_waitcnt lgkmcnt(10)
	v_mfma_f32_16x16x32_bf16 v[28:31], v[132:135], v[104:107], v[28:31]
	v_mfma_f32_16x16x32_bf16 v[36:39], v[132:135], v[108:111], v[36:39]
	s_waitcnt lgkmcnt(8)
	v_mfma_f32_16x16x32_bf16 v[60:63], v[136:139], v[146:149], v[60:63]
	s_waitcnt lgkmcnt(7)
	v_mfma_f32_16x16x32_bf16 v[56:59], v[140:143], v[146:149], v[56:59]
	s_waitcnt lgkmcnt(6)
	v_mfma_f32_16x16x32_bf16 v[24:27], v[136:139], v[150:153], v[24:27]
	v_mfma_f32_16x16x32_bf16 v[20:23], v[140:143], v[150:153], v[20:23]
	s_waitcnt lgkmcnt(5)
	v_mfma_f32_16x16x32_bf16 v[52:55], v[154:157], v[146:149], v[52:55]
	v_mfma_f32_16x16x32_bf16 v[16:19], v[154:157], v[150:153], v[16:19]
	s_waitcnt lgkmcnt(4)
	v_mfma_f32_16x16x32_bf16 v[48:51], v[158:161], v[146:149], v[48:51]
	v_mfma_f32_16x16x32_bf16 v[12:15], v[158:161], v[150:153], v[12:15]
	s_waitcnt lgkmcnt(3)
	v_mfma_f32_16x16x32_bf16 v[44:47], v[162:165], v[146:149], v[44:47]
	v_mfma_f32_16x16x32_bf16 v[8:11], v[162:165], v[150:153], v[8:11]
	s_waitcnt lgkmcnt(2)
	v_mfma_f32_16x16x32_bf16 v[40:43], v[166:169], v[146:149], v[40:43]
	v_mfma_f32_16x16x32_bf16 v[4:7], v[166:169], v[150:153], v[4:7]
	s_waitcnt lgkmcnt(1)
	v_mfma_f32_16x16x32_bf16 v[32:35], v[170:173], v[146:149], v[32:35]
	v_mfma_f32_16x16x32_bf16 v[0:3], v[170:173], v[150:153], v[0:3]
	s_waitcnt lgkmcnt(0)
	v_mfma_f32_16x16x32_bf16 v[28:31], v[174:177], v[146:149], v[28:31]
	v_mfma_f32_16x16x32_bf16 v[36:39], v[174:177], v[150:153], v[36:39]
	s_cbranch_scc0 .LBB0_1824
	v_add_u32_e32 v80, s40, v84
	v_add_u32_e32 v81, v80, v85
	s_waitcnt vmcnt(0)
	s_barrier
	ds_read_b128 v[72:75], v81 offset:16384
	v_add3_u32 v99, s40, v85, v86
	ds_read_b128 v[76:79], v81 offset:18432
	ds_read_b128 v[100:103], v99
	ds_read_b128 v[104:107], v99 offset:2048
	ds_read_b128 v[108:111], v81 offset:20480
	ds_read_b128 v[112:115], v81 offset:22528
	ds_read_b128 v[116:119], v81 offset:24576
	ds_read_b128 v[120:123], v81 offset:26624
	ds_read_b128 v[124:127], v81 offset:28672
	ds_read_b128 v[128:131], v81 offset:30720
	v_add_u32_e32 v80, v80, v87
	s_waitcnt lgkmcnt(7)
	v_mfma_f32_16x16x32_bf16 v[60:63], v[72:75], v[100:103], v[60:63]
	s_lshl_b32 s38, s38, 7
	v_mfma_f32_16x16x32_bf16 v[56:59], v[76:79], v[100:103], v[56:59]
	s_waitcnt lgkmcnt(4)
	v_mfma_f32_16x16x32_bf16 v[48:51], v[112:115], v[100:103], v[48:51]
	s_waitcnt lgkmcnt(3)
	v_mfma_f32_16x16x32_bf16 v[44:47], v[116:119], v[100:103], v[44:47]
	s_waitcnt lgkmcnt(2)
	v_mfma_f32_16x16x32_bf16 v[40:43], v[120:123], v[100:103], v[40:43]
	s_waitcnt lgkmcnt(1)
	v_mfma_f32_16x16x32_bf16 v[32:35], v[124:127], v[100:103], v[32:35]
	s_waitcnt lgkmcnt(0)
	v_mfma_f32_16x16x32_bf16 v[28:31], v[128:131], v[100:103], v[28:31]
	v_mfma_f32_16x16x32_bf16 v[24:27], v[72:75], v[104:107], v[24:27]
	ds_read_b128 v[72:75], v80 offset:16384
	v_mfma_f32_16x16x32_bf16 v[52:55], v[108:111], v[100:103], v[52:55]
	v_mfma_f32_16x16x32_bf16 v[20:23], v[76:79], v[104:107], v[20:23]
	v_mfma_f32_16x16x32_bf16 v[16:19], v[108:111], v[104:107], v[16:19]
	v_mfma_f32_16x16x32_bf16 v[12:15], v[112:115], v[104:107], v[12:15]
	v_mfma_f32_16x16x32_bf16 v[8:11], v[116:119], v[104:107], v[8:11]
	v_mfma_f32_16x16x32_bf16 v[4:7], v[120:123], v[104:107], v[4:7]
	v_mfma_f32_16x16x32_bf16 v[0:3], v[124:127], v[104:107], v[0:3]
	v_mfma_f32_16x16x32_bf16 v[100:103], v[128:131], v[104:107], v[36:39]
	s_nop 2
	v_add3_u32 v36, s40, v87, v86
	ds_read_b128 v[76:79], v80 offset:18432
	ds_read_b128 v[104:107], v36
	ds_read_b128 v[108:111], v36 offset:2048
	ds_read_b128 v[128:131], v80 offset:28672
	ds_read_b128 v[132:135], v80 offset:30720
	ds_read_b128 v[112:115], v80 offset:20480
	ds_read_b128 v[116:119], v80 offset:22528
	ds_read_b128 v[120:123], v80 offset:24576
	ds_read_b128 v[124:127], v80 offset:26624
	s_waitcnt lgkmcnt(7)
	v_mfma_f32_16x16x32_bf16 v[60:63], v[72:75], v[104:107], v[60:63]
	s_waitcnt lgkmcnt(5)
	v_mfma_f32_16x16x32_bf16 v[36:39], v[128:131], v[104:107], v[32:35]
	s_waitcnt lgkmcnt(4)
	v_mfma_f32_16x16x32_bf16 v[32:35], v[132:135], v[104:107], v[28:31]
	v_mfma_f32_16x16x32_bf16 v[28:31], v[72:75], v[108:111], v[24:27]
	v_add_u32_e32 v72, s38, v83
	v_mul_hi_i32 v73, v72, s31
	v_mfma_f32_16x16x32_bf16 v[24:27], v[76:79], v[108:111], v[20:23]
	s_waitcnt lgkmcnt(3)
	v_mfma_f32_16x16x32_bf16 v[20:23], v[112:115], v[108:111], v[16:19]
	s_waitcnt lgkmcnt(2)
	v_mfma_f32_16x16x32_bf16 v[16:19], v[116:119], v[108:111], v[12:15]
	s_waitcnt lgkmcnt(1)
	v_mfma_f32_16x16x32_bf16 v[12:15], v[120:123], v[108:111], v[8:11]
	s_waitcnt lgkmcnt(0)
	v_mfma_f32_16x16x32_bf16 v[8:11], v[124:127], v[108:111], v[4:7]
	s_nop 2
	v_lshrrev_b32_e32 v4, 31, v73
	v_ashrrev_i32_e32 v5, 11, v73
	v_mfma_f32_16x16x32_bf16 v[56:59], v[76:79], v[104:107], v[56:59]
	v_add_u32_e32 v73, v5, v4
	v_mad_i32_i24 v78, v73, s33, v72
	v_lshlrev_b32_e32 v75, 13, v73
	v_mfma_f32_16x16x32_bf16 v[52:55], v[112:115], v[104:107], v[52:55]
	v_cmp_lt_i32_e32 vcc, s34, v78
	v_add3_u32 v74, v75, v78, s35
	v_mfma_f32_16x16x32_bf16 v[48:51], v[116:119], v[104:107], v[48:51]
	v_mfma_f32_16x16x32_bf16 v[44:47], v[120:123], v[104:107], v[44:47]
	v_mfma_f32_16x16x32_bf16 v[40:43], v[124:127], v[104:107], v[40:43]
	v_mfma_f32_16x16x32_bf16 v[4:7], v[128:131], v[108:111], v[0:3]
	v_mfma_f32_16x16x32_bf16 v[0:3], v[132:135], v[108:111], v[100:103]
	s_and_saveexec_b64 s[28:29], vcc
	s_xor_b64 s[28:29], exec, s[28:29]
	v_add3_u32 v72, v75, v78, s35
	s_or_saveexec_b64 s[28:29], s[28:29]
	v_mov_b64_e32 v[76:77], s[92:93]
	v_lshl_add_u32 v75, v73, 8, v78
	s_xor_b64 exec, exec, s[28:29]
	v_lshl_add_u32 v72, v73, 8, v78
	v_mov_b64_e32 v[76:77], s[2:3]
	s_or_b64 exec, exec, s[28:29]
	s_and_saveexec_b64 s[28:29], vcc
	s_xor_b64 s[28:29], exec, s[28:29]
	s_cbranch_execz .LBB0_1831
	v_add_u32_e32 v73, 3, v73
	v_mul_hi_i32_i24_e32 v79, 0x6000, v73
	v_mul_i32_i24_e32 v78, 0x6000, v73
	s_or_saveexec_b64 s[28:29], s[28:29]
	v_mov_b64_e32 v[80:81], s[92:93]
	s_xor_b64 exec, exec, s[28:29]
	s_cbranch_execnz .LBB0_1832
	s_branch .LBB0_1833
